# attention: previous tile's second-half row-sum adds moved into the QK MFMA shadows (split S0/S1 chains)
# baseline (speedup 1.0000x reference)
; #define LAS __attribute__((address_space(3)))
; __device__ __forceinline__ float max3f(float a, float b, float c) { float r; asm("v_max3_f32 %0, %1, %2, %3" : "=v"(r) : "v"(a), "v"(b), "v"(c)); return r; }
; __device__ __forceinline__ void attn_block(LAS unsigned char* lds, const bf16_t* P, bf16_t* mix, int b, int h, int qb, float lam, float outscale, const float* subln) {
;     ...
;         const int kb = 64 * kt;
;         if (kb <= qw0 + 31) {
;             LAS const unsigned char* Kb = lds + ATT_K0 + buf * 16384;
;             LAS const unsigned char* Vb = lds + ATT_V0 + buf * 16384;
;             f32x16 s0, s1;
; #pragma unroll
;             for (int j = 0; j < 16; ++j) { s0[j] = 0.f; s1[j] = 0.f; }
;             bf16x8 ka[4][2];
; #pragma unroll
;             for (int ks = 0; ks < 4; ++ks) { ka[ks][0] = *(const LAS bf16x8*)(Kb + kbase[ks]); ka[ks][1] = *(const LAS bf16x8*)(Kb + kbase[ks] + 8192); }
;             __builtin_amdgcn_sched_barrier(0);
; #pragma unroll
;             for (int ks = 0; ks < 4; ++ks) {
;                 s0 = __builtin_amdgcn_mfma_f32_32x32x16_bf16(ka[ks][0], qf[ks], s0, 0, 0, 0);
;                 s1 = __builtin_amdgcn_mfma_f32_32x32x16_bf16(ka[ks][1], qf[ks], s1, 0, 0, 0);
;             }
;             if (kb + 63 > qw0) {
; #pragma unroll
;                 for (int j = 0; j < 16; ++j) { const int key = kb + crow(j, hi); if (key > qrow) s0[j] = -INFINITY; if (key + 32 > qrow) s1[j] = -INFINITY; }
;             }
;             float mxa = max3f(s0[0], s1[0], s0[1]), mxb = max3f(s1[1], s0[2], s1[2]), mxc = max3f(s0[3], s1[3], s0[4]), mxd = max3f(s1[4], s0[5], s1[5]);
;             mxa = max3f(mxa, s0[6], s1[6]); mxb = max3f(mxb, s0[7], s1[7]); mxc = max3f(mxc, s0[8], s1[8]); mxd = max3f(mxd, s0[9], s1[9]);
;             mxa = max3f(mxa, s0[10], s1[10]); mxb = max3f(mxb, s0[11], s1[11]); mxc = max3f(mxc, s0[12], s1[12]); mxd = max3f(mxd, s0[13], s1[13]);
;             mxa = max3f(mxa, s0[14], s1[14]); mxb = max3f(mxb, s0[15], s1[15]);
;             float mx = max3f(mxa, mxb, max3f(mxc, mxd, mxd));
;             { auto rr = __builtin_amdgcn_permlane32_swap(__builtin_bit_cast(unsigned, mx), __builtin_bit_cast(unsigned, mx), false, false);
;               mx = fmaxf(__builtin_bit_cast(float, rr[0]), __builtin_bit_cast(float, rr[1])); }
;             if (__any(mx > mrun + 8.0f)) {
.Lat1_pre_done:
	s_waitcnt lgkmcnt(0)
	s_barrier
	ds_read_b128 v[136:139], v180
	ds_read_b128 v[140:143], v180 offset:8192
	ds_read_b128 v[204:207], v181
	ds_read_b128 v[208:211], v181 offset:8192
	ds_read_b128 v[238:241], v178
	ds_read_b128 v[242:245], v178 offset:8192
	ds_read_b128 v[246:249], v177
	ds_read_b128 v[250:253], v177 offset:8192
	s_add_i32 s73, s71, 384
	s_cmp_le_u32 s73, s36
	s_cbranch_scc0 .Lat1_U_none
	v_add_u32_e32 v114, 0x10000, v173
	v_add_u32_e32 v115, 0x10000, v174
	v_add_u32_e32 v116, 0x10000, v170
	v_add_u32_e32 v117, 0x10000, v172
	v_add_u32_e32 v118, 0x10000, v168
	v_add_u32_e32 v119, 0x10000, v171
	v_add_u32_e32 v120, 0x10000, v145
	v_add_u32_e32 v121, 0x10000, v169
	v_add_u32_e32 v126, 0x10000, v180
	v_add_u32_e32 v127, 0x10000, v181
	v_add_u32_e32 v128, 0x10000, v178
	v_add_u32_e32 v129, 0x10000, v177
	s_lshl_b32 s70, s42, 4
	s_and_b32 s70, s70, 0x1c00
	s_mov_b32 s73, s70
	v_mov_b32_e32 v66, 0
	v_mov_b32_e32 v67, 0
	v_mov_b32_e32 v68, 0
	v_mov_b32_e32 v69, 0
	v_mov_b32_e32 v70, 0
	v_mov_b32_e32 v71, 0
	v_mov_b32_e32 v72, 0
	v_mov_b32_e32 v73, 0
	v_mov_b32_e32 v74, 0
	v_mov_b32_e32 v75, 0
	v_mov_b32_e32 v76, 0
	v_mov_b32_e32 v77, 0
	v_mov_b32_e32 v78, 0
	v_mov_b32_e32 v79, 0
	v_mov_b32_e32 v80, 0
	v_mov_b32_e32 v81, 0
.Lat1_U_top:
	s_add_i32 m0, s73, 0x14000
	s_nop 0
	global_load_lds_dwordx4 v[134:135], off
	s_add_i32 m0, s73, 0x16000
	s_nop 0
	global_load_lds_dwordx4 v[200:201], off
	s_waitcnt lgkmcnt(7)
	v_mfma_f32_32x32x16_bf16 v[82:97], v[136:139], v[110:113], v[222:237]
	v_add_f32_e32 v122, v66, v67
	v_add_f32_e32 v123, v68, v69
	v_add_f32_e32 v122, v122, v70
	v_add_f32_e32 v123, v123, v71
	s_waitcnt lgkmcnt(5)
	v_mfma_f32_32x32x16_bf16 v[82:97], v[204:207], v[106:109], v[82:97]
	v_add_f32_e32 v122, v122, v72
	v_add_f32_e32 v123, v123, v73
	v_add_f32_e32 v122, v122, v123
	v_add_f32_e32 v167, v167, v122
	s_waitcnt lgkmcnt(3)
	v_mfma_f32_32x32x16_bf16 v[82:97], v[238:241], v[102:105], v[82:97]
	v_add_f32_e32 v122, v74, v75
	v_add_f32_e32 v123, v76, v77
	v_add_f32_e32 v122, v122, v78
	v_add_f32_e32 v123, v123, v79
	s_waitcnt lgkmcnt(1)
	v_mfma_f32_32x32x16_bf16 v[82:97], v[246:249], v[98:101], v[82:97]
	v_add_f32_e32 v122, v122, v80
	v_add_f32_e32 v123, v123, v81
	v_add_f32_e32 v122, v122, v123
	v_add_f32_e32 v167, v167, v122
	s_waitcnt lgkmcnt(0)
	v_mfma_f32_32x32x16_bf16 v[66:81], v[140:143], v[110:113], v[222:237]
	v_mfma_f32_32x32x16_bf16 v[66:81], v[208:211], v[106:109], v[66:81]
	v_mfma_f32_32x32x16_bf16 v[66:81], v[242:245], v[102:105], v[66:81]
	v_mfma_f32_32x32x16_bf16 v[66:81], v[250:253], v[98:101], v[66:81]
	ds_read_b64_tr_b16 v[136:137], v173 offset:32768
	ds_read_b64_tr_b16 v[138:139], v174 offset:32768
	ds_read_b64_tr_b16 v[140:141], v170 offset:32768
	ds_read_b64_tr_b16 v[142:143], v172 offset:32768
	ds_read_b64_tr_b16 v[204:205], v168 offset:32768
	ds_read_b64_tr_b16 v[206:207], v171 offset:32768
	ds_read_b64_tr_b16 v[208:209], v145 offset:32768
	ds_read_b64_tr_b16 v[210:211], v169 offset:32768
	ds_read_b64_tr_b16 v[238:239], v173 offset:36864
	ds_read_b64_tr_b16 v[240:241], v174 offset:36864
	ds_read_b64_tr_b16 v[242:243], v170 offset:36864
	ds_read_b64_tr_b16 v[244:245], v172 offset:36864
	s_nop 1
	v_max3_f32 v122, v82, v66, v83
	v_max3_f32 v123, v67, v84, v68
	v_max3_f32 v124, v85, v69, v86
	v_max3_f32 v125, v70, v87, v71
	v_max3_f32 v122, v122, v88, v72
	v_max3_f32 v123, v123, v89, v73
	v_max3_f32 v124, v124, v90, v74
	v_max3_f32 v125, v125, v91, v75
	v_max3_f32 v122, v122, v92, v76
	v_max3_f32 v123, v123, v93, v77
	v_max3_f32 v124, v124, v94, v78
	v_max3_f32 v125, v125, v95, v79
	v_max3_f32 v122, v122, v96, v80
	v_max3_f32 v123, v123, v97, v81
	v_max3_f32 v122, v122, v123, v124
	v_max_f32_e32 v122, v122, v125
	v_mov_b32_e32 v203, v122
	s_nop 1
	v_permlane32_swap_b32_e32 v122, v203
	s_nop 1
	v_max_f32_e32 v122, v122, v203
	s_mov_b32 s70, 0
	v_cmp_lt_f32_e32 vcc, 0x41000000, v122
	s_cmp_eq_u32 s71, 0
	s_cbranch_scc1 .Lat1_u0_first
	s_cbranch_vccz .Lat1_u0_norescale
	s_branch .Lat1_u0_rescale

; __device__ __forceinline__ unsigned pk2(float lo, float hi) { f32x2 v = {lo, hi}; bf16x2_t b = __builtin_convertvector(v, bf16x2_t); return __builtin_bit_cast(unsigned, b); }
; __device__ __forceinline__ s16x4 vtr(LAS const unsigned char* p) { return __builtin_bit_cast(s16x4, __builtin_amdgcn_ds_read_tr16_b64_v4i16((LAS v4i16_t*)p)); }
; __device__ __forceinline__ bf16x8 cat8(s16x4 a, s16x4 b) { return (bf16x8){a[0], a[1], a[2], a[3], b[0], b[1], b[2], b[3]}; }
; __device__ __forceinline__ void attn_block(LAS unsigned char* lds, const bf16_t* P, bf16_t* mix, int b, int h, int qb, float lam, float outscale, const float* subln) {
;     ...
;             for (int j = 0; j < 16; ++j) { s0[j] = __builtin_amdgcn_exp2f(s0[j] - mrun); s1[j] = __builtin_amdgcn_exp2f(s1[j] - mrun); }
;             float ps0 = 0.f, ps1 = 0.f, ps2 = 0.f, ps3 = 0.f;
; #pragma unroll
;             for (int j = 0; j < 16; j += 2) { ps0 += s0[j]; ps1 += s1[j]; ps2 += s0[j + 1]; ps3 += s1[j + 1]; }
;             lrun += (ps0 + ps1) + (ps2 + ps3);
;             bf16x8 pb[4];
; #pragma unroll
;             for (int s2 = 0; s2 < 2; ++s2) {
;                 u32x4 w0, w1;
;                 w0.x = pk2(s0[8 * s2 + 0], s0[8 * s2 + 1]); w0.y = pk2(s0[8 * s2 + 2], s0[8 * s2 + 3]); w0.z = pk2(s0[8 * s2 + 4], s0[8 * s2 + 5]); w0.w = pk2(s0[8 * s2 + 6], s0[8 * s2 + 7]);
;                 w1.x = pk2(s1[8 * s2 + 0], s1[8 * s2 + 1]); w1.y = pk2(s1[8 * s2 + 2], s1[8 * s2 + 3]); w1.z = pk2(s1[8 * s2 + 4], s1[8 * s2 + 5]); w1.w = pk2(s1[8 * s2 + 6], s1[8 * s2 + 7]);
;                 pb[s2] = __builtin_bit_cast(bf16x8, w0); pb[2 + s2] = __builtin_bit_cast(bf16x8, w1);
;             }
; #pragma unroll
;             for (int s = 0; s < 4; ++s) {
; #pragma unroll
;                 for (int c = 0; c < 4; ++c) {
;                     const s16x4 v0 = vtr(Vb + vbase[c][0] + 4096 * s);
;                     const s16x4 v1 = vtr(Vb + vbase[c][1] + 4096 * s);
;                     o[c] = __builtin_amdgcn_mfma_f32_32x32x16_bf16(cat8(v0, v1), pb[s], o[c], 0, 0, 0);
;                 }
;             }
.Lat1_u0_norescale:
	v_exp_f32_e32 v82, v82
	v_exp_f32_e32 v83, v83
	v_exp_f32_e32 v84, v84
	v_exp_f32_e32 v85, v85
	v_exp_f32_e32 v86, v86
	v_exp_f32_e32 v87, v87
	v_exp_f32_e32 v88, v88
	v_exp_f32_e32 v89, v89
	v_exp_f32_e32 v90, v90
	v_exp_f32_e32 v91, v91
	v_exp_f32_e32 v92, v92
	v_exp_f32_e32 v93, v93
	v_exp_f32_e32 v94, v94
	v_exp_f32_e32 v95, v95
	v_exp_f32_e32 v96, v96
	v_exp_f32_e32 v97, v97
	v_cvt_pk_bf16_f32 v184, v82, v83
	v_cvt_pk_bf16_f32 v185, v84, v85
	v_cvt_pk_bf16_f32 v186, v86, v87
	v_cvt_pk_bf16_f32 v187, v88, v89
	v_cvt_pk_bf16_f32 v188, v90, v91
	v_cvt_pk_bf16_f32 v189, v92, v93
	v_cvt_pk_bf16_f32 v190, v94, v95
	v_cvt_pk_bf16_f32 v191, v96, v97
	v_add_f32_e32 v122, v82, v83
	v_add_f32_e32 v123, v84, v85
	v_add_f32_e32 v122, v122, v86
	v_add_f32_e32 v123, v123, v87
	v_add_f32_e32 v122, v122, v88
	v_add_f32_e32 v123, v123, v89
	v_add_f32_e32 v122, v122, v123
	v_add_f32_e32 v167, v167, v122
	v_add_f32_e32 v124, v90, v91
	v_add_f32_e32 v125, v92, v93
	v_add_f32_e32 v124, v124, v94
	v_add_f32_e32 v125, v125, v95
	v_add_f32_e32 v124, v124, v96
	v_add_f32_e32 v125, v125, v97
	v_add_f32_e32 v124, v124, v125
	v_add_f32_e32 v167, v167, v124
	s_add_i32 m0, s73, 0x1b800
	s_nop 0
	global_load_lds_dwordx4 v[134:135], off offset:2048
	s_add_i32 m0, s73, 0x1d800
	s_nop 0
	global_load_lds_dwordx4 v[200:201], off offset:2048
	v_lshl_add_u64 v[134:135], v[134:135], 0, s[40:41]
	v_lshl_add_u64 v[200:201], v[200:201], 0, s[40:41]
	s_waitcnt lgkmcnt(8)
	v_mfma_f32_32x32x16_bf16 v[50:65], v[136:139], v[184:187], v[50:65]
	ds_read_b64_tr_b16 v[246:247], v168 offset:36864
	ds_read_b64_tr_b16 v[248:249], v171 offset:36864
	v_exp_f32_e32 v66, v66
	v_exp_f32_e32 v67, v67
	v_exp_f32_e32 v68, v68
	v_mfma_f32_32x32x16_bf16 v[34:49], v[140:143], v[184:187], v[34:49]
	ds_read_b64_tr_b16 v[250:251], v145 offset:36864
	ds_read_b64_tr_b16 v[252:253], v169 offset:36864
	v_exp_f32_e32 v69, v69
	v_exp_f32_e32 v70, v70
	v_exp_f32_e32 v71, v71
	s_waitcnt lgkmcnt(8)
	v_mfma_f32_32x32x16_bf16 v[18:33], v[204:207], v[184:187], v[18:33]
	ds_read_b64_tr_b16 v[136:137], v173 offset:40960
	ds_read_b64_tr_b16 v[138:139], v174 offset:40960
	v_exp_f32_e32 v72, v72
	v_exp_f32_e32 v73, v73
	v_cvt_pk_bf16_f32 v192, v66, v67
	v_mfma_f32_32x32x16_bf16 v[2:17], v[208:211], v[184:187], v[2:17]
	ds_read_b64_tr_b16 v[140:141], v170 offset:40960
	ds_read_b64_tr_b16 v[142:143], v172 offset:40960
	v_cvt_pk_bf16_f32 v193, v68, v69
	v_cvt_pk_bf16_f32 v194, v70, v71
	v_cvt_pk_bf16_f32 v195, v72, v73
	s_waitcnt lgkmcnt(8)
	v_mfma_f32_32x32x16_bf16 v[50:65], v[238:241], v[188:191], v[50:65]
	ds_read_b64_tr_b16 v[204:205], v168 offset:40960
	ds_read_b64_tr_b16 v[206:207], v171 offset:40960
	v_exp_f32_e32 v74, v74
	v_exp_f32_e32 v75, v75
	v_exp_f32_e32 v76, v76
	v_mfma_f32_32x32x16_bf16 v[34:49], v[242:245], v[188:191], v[34:49]
	ds_read_b64_tr_b16 v[208:209], v145 offset:40960
	ds_read_b64_tr_b16 v[210:211], v169 offset:40960
	v_exp_f32_e32 v77, v77
	v_exp_f32_e32 v78, v78
	v_exp_f32_e32 v79, v79
	s_waitcnt lgkmcnt(8)
	v_mfma_f32_32x32x16_bf16 v[18:33], v[246:249], v[188:191], v[18:33]
	ds_read_b64_tr_b16 v[238:239], v173 offset:45056
	ds_read_b64_tr_b16 v[240:241], v174 offset:45056
	v_exp_f32_e32 v80, v80
	v_exp_f32_e32 v81, v81
	v_cvt_pk_bf16_f32 v196, v74, v75
	v_mfma_f32_32x32x16_bf16 v[2:17], v[250:253], v[188:191], v[2:17]
	ds_read_b64_tr_b16 v[242:243], v170 offset:45056
	ds_read_b64_tr_b16 v[244:245], v172 offset:45056
	v_cvt_pk_bf16_f32 v197, v76, v77
	v_cvt_pk_bf16_f32 v198, v78, v79
	v_cvt_pk_bf16_f32 v199, v80, v81
	s_waitcnt lgkmcnt(8)
	v_mfma_f32_32x32x16_bf16 v[50:65], v[136:139], v[192:195], v[50:65]
	ds_read_b64_tr_b16 v[246:247], v168 offset:45056
	ds_read_b64_tr_b16 v[248:249], v171 offset:45056
	v_mfma_f32_32x32x16_bf16 v[34:49], v[140:143], v[192:195], v[34:49]
	ds_read_b64_tr_b16 v[250:251], v145 offset:45056
	ds_read_b64_tr_b16 v[252:253], v169 offset:45056
	s_waitcnt lgkmcnt(8)
	v_mfma_f32_32x32x16_bf16 v[18:33], v[204:207], v[192:195], v[18:33]
	v_mfma_f32_32x32x16_bf16 v[2:17], v[208:211], v[192:195], v[2:17]
	s_waitcnt lgkmcnt(4)
	v_mfma_f32_32x32x16_bf16 v[50:65], v[238:241], v[196:199], v[50:65]
	v_mfma_f32_32x32x16_bf16 v[34:49], v[242:245], v[196:199], v[34:49]
	s_waitcnt lgkmcnt(0)
	v_mfma_f32_32x32x16_bf16 v[18:33], v[246:249], v[196:199], v[18:33]
	v_mfma_f32_32x32x16_bf16 v[2:17], v[250:253], v[196:199], v[2:17]
	ds_read_b128 v[136:139], v180 offset:16384
	ds_read_b128 v[140:143], v180 offset:24576
	ds_read_b128 v[204:207], v181 offset:16384
	ds_read_b128 v[208:211], v181 offset:24576
	ds_read_b128 v[238:241], v178 offset:16384
	ds_read_b128 v[242:245], v178 offset:24576
	ds_read_b128 v[246:249], v177 offset:16384
	ds_read_b128 v[250:253], v177 offset:24576
	s_waitcnt vmcnt(6)
	s_add_i32 s71, s71, 64
	s_barrier
; #define LAS __attribute__((address_space(3)))
; __device__ __forceinline__ float max3f(float a, float b, float c) { float r; asm("v_max3_f32 %0, %1, %2, %3" : "=v"(r) : "v"(a), "v"(b), "v"(c)); return r; }
; __device__ __forceinline__ int crow(int r, int hi) { return (r & 3) + 8 * (r >> 2) + 4 * hi; }
; __device__ __forceinline__ void attn_block(LAS unsigned char* lds, const bf16_t* P, bf16_t* mix, int b, int h, int qb, float lam, float outscale, const float* subln) {
;     ...
;             f32x16 s0, s1;
; #pragma unroll
;             for (int j = 0; j < 16; ++j) { s0[j] = 0.f; s1[j] = 0.f; }
;             bf16x8 ka[4][2];
; #pragma unroll
;             for (int ks = 0; ks < 4; ++ks) { ka[ks][0] = *(const LAS bf16x8*)(Kb + kbase[ks]); ka[ks][1] = *(const LAS bf16x8*)(Kb + kbase[ks] + 8192); }
;             __builtin_amdgcn_sched_barrier(0);
; #pragma unroll
;             for (int ks = 0; ks < 4; ++ks) {
;                 s0 = __builtin_amdgcn_mfma_f32_32x32x16_bf16(ka[ks][0], qf[ks], s0, 0, 0, 0);
;                 s1 = __builtin_amdgcn_mfma_f32_32x32x16_bf16(ka[ks][1], qf[ks], s1, 0, 0, 0);
;             }
;             if (kb + 63 > qw0) {
; #pragma unroll
;                 for (int j = 0; j < 16; ++j) { const int key = kb + crow(j, hi); if (key > qrow) s0[j] = -INFINITY; if (key + 32 > qrow) s1[j] = -INFINITY; }
;             }
;             float mxa = max3f(s0[0], s1[0], s0[1]), mxb = max3f(s1[1], s0[2], s1[2]), mxc = max3f(s0[3], s1[3], s0[4]), mxd = max3f(s1[4], s0[5], s1[5]);
;             mxa = max3f(mxa, s0[6], s1[6]); mxb = max3f(mxb, s0[7], s1[7]); mxc = max3f(mxc, s0[8], s1[8]); mxd = max3f(mxd, s0[9], s1[9]);
;             mxa = max3f(mxa, s0[10], s1[10]); mxb = max3f(mxb, s0[11], s1[11]); mxc = max3f(mxc, s0[12], s1[12]); mxd = max3f(mxd, s0[13], s1[13]);
;             mxa = max3f(mxa, s0[14], s1[14]); mxb = max3f(mxb, s0[15], s1[15]);
;             float mx = max3f(mxa, mxb, max3f(mxc, mxd, mxd));
;             { auto rr = __builtin_amdgcn_permlane32_swap(__builtin_bit_cast(unsigned, mx), __builtin_bit_cast(unsigned, mx), false, false);
;               mx = fmaxf(__builtin_bit_cast(float, rr[0]), __builtin_bit_cast(float, rr[1])); }
;             if (__any(mx > mrun + 8.0f)) {
	s_add_i32 m0, s73, 0x0
	s_nop 0
	global_load_lds_dwordx4 v[134:135], off
	s_add_i32 m0, s73, 0x2000
	s_nop 0
	global_load_lds_dwordx4 v[200:201], off
	s_waitcnt lgkmcnt(7)
	v_mfma_f32_32x32x16_bf16 v[82:97], v[136:139], v[110:113], v[222:237]
	v_add_f32_e32 v122, v66, v67
	v_add_f32_e32 v123, v68, v69
	v_add_f32_e32 v122, v122, v70
	v_add_f32_e32 v123, v123, v71
	s_waitcnt lgkmcnt(5)
	v_mfma_f32_32x32x16_bf16 v[82:97], v[204:207], v[106:109], v[82:97]
	v_add_f32_e32 v122, v122, v72
	v_add_f32_e32 v123, v123, v73
	v_add_f32_e32 v122, v122, v123
	v_add_f32_e32 v167, v167, v122
	s_waitcnt lgkmcnt(3)
	v_mfma_f32_32x32x16_bf16 v[82:97], v[238:241], v[102:105], v[82:97]
	v_add_f32_e32 v122, v74, v75
	v_add_f32_e32 v123, v76, v77
	v_add_f32_e32 v122, v122, v78
	v_add_f32_e32 v123, v123, v79
	s_waitcnt lgkmcnt(1)
	v_mfma_f32_32x32x16_bf16 v[82:97], v[246:249], v[98:101], v[82:97]
	v_add_f32_e32 v122, v122, v80
	v_add_f32_e32 v123, v123, v81
	v_add_f32_e32 v122, v122, v123
	v_add_f32_e32 v167, v167, v122
	s_waitcnt lgkmcnt(0)
	v_mfma_f32_32x32x16_bf16 v[66:81], v[140:143], v[110:113], v[222:237]
	v_mfma_f32_32x32x16_bf16 v[66:81], v[208:211], v[106:109], v[66:81]
	v_mfma_f32_32x32x16_bf16 v[66:81], v[242:245], v[102:105], v[66:81]
	v_mfma_f32_32x32x16_bf16 v[66:81], v[250:253], v[98:101], v[66:81]
	ds_read_b64_tr_b16 v[136:137], v173 offset:49152
	ds_read_b64_tr_b16 v[138:139], v174 offset:49152
	ds_read_b64_tr_b16 v[140:141], v170 offset:49152
	ds_read_b64_tr_b16 v[142:143], v172 offset:49152
	ds_read_b64_tr_b16 v[204:205], v168 offset:49152
	ds_read_b64_tr_b16 v[206:207], v171 offset:49152
	ds_read_b64_tr_b16 v[208:209], v145 offset:49152
	ds_read_b64_tr_b16 v[210:211], v169 offset:49152
	ds_read_b64_tr_b16 v[238:239], v173 offset:53248
	ds_read_b64_tr_b16 v[240:241], v174 offset:53248
	ds_read_b64_tr_b16 v[242:243], v170 offset:53248
	ds_read_b64_tr_b16 v[244:245], v172 offset:53248
	s_nop 1
	v_max3_f32 v122, v82, v66, v83
	v_max3_f32 v123, v67, v84, v68
	v_max3_f32 v124, v85, v69, v86
	v_max3_f32 v125, v70, v87, v71
	v_max3_f32 v122, v122, v88, v72
	v_max3_f32 v123, v123, v89, v73
	v_max3_f32 v124, v124, v90, v74
	v_max3_f32 v125, v125, v91, v75
	v_max3_f32 v122, v122, v92, v76
	v_max3_f32 v123, v123, v93, v77
	v_max3_f32 v124, v124, v94, v78
	v_max3_f32 v125, v125, v95, v79
	v_max3_f32 v122, v122, v96, v80
	v_max3_f32 v123, v123, v97, v81
	v_max3_f32 v122, v122, v123, v124
	v_max_f32_e32 v122, v122, v125
	v_mov_b32_e32 v203, v122
	s_nop 1
	v_permlane32_swap_b32_e32 v122, v203
	s_nop 1
	v_max_f32_e32 v122, v122, v203
	s_mov_b32 s70, 0
	v_cmp_lt_f32_e32 vcc, 0x41000000, v122
	s_cmp_eq_u32 s71, 0
	s_cbranch_scc1 .Lat1_u1_first
	s_cbranch_vccz .Lat1_u1_norescale
	s_branch .Lat1_u1_rescale

; __device__ __forceinline__ unsigned pk2(float lo, float hi) { f32x2 v = {lo, hi}; bf16x2_t b = __builtin_convertvector(v, bf16x2_t); return __builtin_bit_cast(unsigned, b); }
; __device__ __forceinline__ s16x4 vtr(LAS const unsigned char* p) { return __builtin_bit_cast(s16x4, __builtin_amdgcn_ds_read_tr16_b64_v4i16((LAS v4i16_t*)p)); }
; __device__ __forceinline__ bf16x8 cat8(s16x4 a, s16x4 b) { return (bf16x8){a[0], a[1], a[2], a[3], b[0], b[1], b[2], b[3]}; }
; __device__ __forceinline__ void attn_block(LAS unsigned char* lds, const bf16_t* P, bf16_t* mix, int b, int h, int qb, float lam, float outscale, const float* subln) {
;     ...
;             for (int j = 0; j < 16; ++j) { s0[j] = __builtin_amdgcn_exp2f(s0[j] - mrun); s1[j] = __builtin_amdgcn_exp2f(s1[j] - mrun); }
;             float ps0 = 0.f, ps1 = 0.f, ps2 = 0.f, ps3 = 0.f;
; #pragma unroll
;             for (int j = 0; j < 16; j += 2) { ps0 += s0[j]; ps1 += s1[j]; ps2 += s0[j + 1]; ps3 += s1[j + 1]; }
;             lrun += (ps0 + ps1) + (ps2 + ps3);
;             bf16x8 pb[4];
; #pragma unroll
;             for (int s2 = 0; s2 < 2; ++s2) {
;                 u32x4 w0, w1;
;                 w0.x = pk2(s0[8 * s2 + 0], s0[8 * s2 + 1]); w0.y = pk2(s0[8 * s2 + 2], s0[8 * s2 + 3]); w0.z = pk2(s0[8 * s2 + 4], s0[8 * s2 + 5]); w0.w = pk2(s0[8 * s2 + 6], s0[8 * s2 + 7]);
;                 w1.x = pk2(s1[8 * s2 + 0], s1[8 * s2 + 1]); w1.y = pk2(s1[8 * s2 + 2], s1[8 * s2 + 3]); w1.z = pk2(s1[8 * s2 + 4], s1[8 * s2 + 5]); w1.w = pk2(s1[8 * s2 + 6], s1[8 * s2 + 7]);
;                 pb[s2] = __builtin_bit_cast(bf16x8, w0); pb[2 + s2] = __builtin_bit_cast(bf16x8, w1);
;             }
; #pragma unroll
;             for (int s = 0; s < 4; ++s) {
; #pragma unroll
;                 for (int c = 0; c < 4; ++c) {
;                     const s16x4 v0 = vtr(Vb + vbase[c][0] + 4096 * s);
;                     const s16x4 v1 = vtr(Vb + vbase[c][1] + 4096 * s);
;                     o[c] = __builtin_amdgcn_mfma_f32_32x32x16_bf16(cat8(v0, v1), pb[s], o[c], 0, 0, 0);
;                 }
;             }
.Lat1_u1_norescale:
	v_exp_f32_e32 v82, v82
	v_exp_f32_e32 v83, v83
	v_exp_f32_e32 v84, v84
	v_exp_f32_e32 v85, v85
	v_exp_f32_e32 v86, v86
	v_exp_f32_e32 v87, v87
	v_exp_f32_e32 v88, v88
	v_exp_f32_e32 v89, v89
	v_exp_f32_e32 v90, v90
	v_exp_f32_e32 v91, v91
	v_exp_f32_e32 v92, v92
	v_exp_f32_e32 v93, v93
	v_exp_f32_e32 v94, v94
	v_exp_f32_e32 v95, v95
	v_exp_f32_e32 v96, v96
	v_exp_f32_e32 v97, v97
	v_cvt_pk_bf16_f32 v184, v82, v83
	v_cvt_pk_bf16_f32 v185, v84, v85
	v_cvt_pk_bf16_f32 v186, v86, v87
	v_cvt_pk_bf16_f32 v187, v88, v89
	v_cvt_pk_bf16_f32 v188, v90, v91
	v_cvt_pk_bf16_f32 v189, v92, v93
	v_cvt_pk_bf16_f32 v190, v94, v95
	v_cvt_pk_bf16_f32 v191, v96, v97
	v_add_f32_e32 v122, v82, v83
	v_add_f32_e32 v123, v84, v85
	v_add_f32_e32 v122, v122, v86
	v_add_f32_e32 v123, v123, v87
	v_add_f32_e32 v122, v122, v88
	v_add_f32_e32 v123, v123, v89
	v_add_f32_e32 v122, v122, v123
	v_add_f32_e32 v167, v167, v122
	v_add_f32_e32 v124, v90, v91
	v_add_f32_e32 v125, v92, v93
	v_add_f32_e32 v124, v124, v94
	v_add_f32_e32 v125, v125, v95
	v_add_f32_e32 v124, v124, v96
	v_add_f32_e32 v125, v125, v97
	v_add_f32_e32 v124, v124, v125
	v_add_f32_e32 v167, v167, v124
	s_add_i32 m0, s73, 0x7800
	s_nop 0
	global_load_lds_dwordx4 v[134:135], off offset:2048
	s_add_i32 m0, s73, 0x9800
	s_nop 0
	global_load_lds_dwordx4 v[200:201], off offset:2048
	v_lshl_add_u64 v[134:135], v[134:135], 0, s[40:41]
	v_lshl_add_u64 v[200:201], v[200:201], 0, s[40:41]
	s_waitcnt lgkmcnt(8)
	v_mfma_f32_32x32x16_bf16 v[50:65], v[136:139], v[184:187], v[50:65]
	ds_read_b64_tr_b16 v[246:247], v168 offset:53248
	ds_read_b64_tr_b16 v[248:249], v171 offset:53248
	v_exp_f32_e32 v66, v66
	v_exp_f32_e32 v67, v67
	v_exp_f32_e32 v68, v68
	v_mfma_f32_32x32x16_bf16 v[34:49], v[140:143], v[184:187], v[34:49]
	ds_read_b64_tr_b16 v[250:251], v145 offset:53248
	ds_read_b64_tr_b16 v[252:253], v169 offset:53248
	v_exp_f32_e32 v69, v69
	v_exp_f32_e32 v70, v70
	v_exp_f32_e32 v71, v71
	s_waitcnt lgkmcnt(8)
	v_mfma_f32_32x32x16_bf16 v[18:33], v[204:207], v[184:187], v[18:33]
	ds_read_b64_tr_b16 v[136:137], v173 offset:57344
	ds_read_b64_tr_b16 v[138:139], v174 offset:57344
	v_exp_f32_e32 v72, v72
	v_exp_f32_e32 v73, v73
	v_cvt_pk_bf16_f32 v192, v66, v67
	v_mfma_f32_32x32x16_bf16 v[2:17], v[208:211], v[184:187], v[2:17]
	ds_read_b64_tr_b16 v[140:141], v170 offset:57344
	ds_read_b64_tr_b16 v[142:143], v172 offset:57344
	v_cvt_pk_bf16_f32 v193, v68, v69
	v_cvt_pk_bf16_f32 v194, v70, v71
	v_cvt_pk_bf16_f32 v195, v72, v73
	s_waitcnt lgkmcnt(8)
	v_mfma_f32_32x32x16_bf16 v[50:65], v[238:241], v[188:191], v[50:65]
	ds_read_b64_tr_b16 v[204:205], v168 offset:57344
	ds_read_b64_tr_b16 v[206:207], v171 offset:57344
	v_exp_f32_e32 v74, v74
	v_exp_f32_e32 v75, v75
	v_exp_f32_e32 v76, v76
	v_mfma_f32_32x32x16_bf16 v[34:49], v[242:245], v[188:191], v[34:49]
	ds_read_b64_tr_b16 v[208:209], v145 offset:57344
	ds_read_b64_tr_b16 v[210:211], v169 offset:57344
	v_exp_f32_e32 v77, v77
	v_exp_f32_e32 v78, v78
	v_exp_f32_e32 v79, v79
	s_waitcnt lgkmcnt(8)
	v_mfma_f32_32x32x16_bf16 v[18:33], v[246:249], v[188:191], v[18:33]
	ds_read_b64_tr_b16 v[238:239], v173 offset:61440
	ds_read_b64_tr_b16 v[240:241], v174 offset:61440
	v_exp_f32_e32 v80, v80
	v_exp_f32_e32 v81, v81
	v_cvt_pk_bf16_f32 v196, v74, v75
	v_mfma_f32_32x32x16_bf16 v[2:17], v[250:253], v[188:191], v[2:17]
	ds_read_b64_tr_b16 v[242:243], v170 offset:61440
	ds_read_b64_tr_b16 v[244:245], v172 offset:61440
	v_cvt_pk_bf16_f32 v197, v76, v77
	v_cvt_pk_bf16_f32 v198, v78, v79
	v_cvt_pk_bf16_f32 v199, v80, v81
	s_waitcnt lgkmcnt(8)
	v_mfma_f32_32x32x16_bf16 v[50:65], v[136:139], v[192:195], v[50:65]
	ds_read_b64_tr_b16 v[246:247], v168 offset:61440
	ds_read_b64_tr_b16 v[248:249], v171 offset:61440
	v_mfma_f32_32x32x16_bf16 v[34:49], v[140:143], v[192:195], v[34:49]
	ds_read_b64_tr_b16 v[250:251], v145 offset:61440
	ds_read_b64_tr_b16 v[252:253], v169 offset:61440
	s_waitcnt lgkmcnt(8)
	v_mfma_f32_32x32x16_bf16 v[18:33], v[204:207], v[192:195], v[18:33]
	v_mfma_f32_32x32x16_bf16 v[2:17], v[208:211], v[192:195], v[2:17]
	s_waitcnt lgkmcnt(4)
	v_mfma_f32_32x32x16_bf16 v[50:65], v[238:241], v[196:199], v[50:65]
	v_mfma_f32_32x32x16_bf16 v[34:49], v[242:245], v[196:199], v[34:49]
	s_waitcnt lgkmcnt(0)
	v_mfma_f32_32x32x16_bf16 v[18:33], v[246:249], v[196:199], v[18:33]
	v_mfma_f32_32x32x16_bf16 v[2:17], v[250:253], v[196:199], v[2:17]
	ds_read_b128 v[136:139], v126 offset:0
	ds_read_b128 v[140:143], v126 offset:8192
	ds_read_b128 v[204:207], v127 offset:0
	ds_read_b128 v[208:211], v127 offset:8192
	ds_read_b128 v[238:241], v128 offset:0
	ds_read_b128 v[242:245], v128 offset:8192
	ds_read_b128 v[246:249], v129 offset:0
	ds_read_b128 v[250:253], v129 offset:8192
	s_waitcnt vmcnt(6)
	s_add_i32 s71, s71, 64
	s_barrier
; #define LAS __attribute__((address_space(3)))
; __device__ __forceinline__ float max3f(float a, float b, float c) { float r; asm("v_max3_f32 %0, %1, %2, %3" : "=v"(r) : "v"(a), "v"(b), "v"(c)); return r; }
; __device__ __forceinline__ int crow(int r, int hi) { return (r & 3) + 8 * (r >> 2) + 4 * hi; }
; __device__ __forceinline__ void attn_block(LAS unsigned char* lds, const bf16_t* P, bf16_t* mix, int b, int h, int qb, float lam, float outscale, const float* subln) {
;     ...
;             f32x16 s0, s1;
; #pragma unroll
;             for (int j = 0; j < 16; ++j) { s0[j] = 0.f; s1[j] = 0.f; }
;             bf16x8 ka[4][2];
; #pragma unroll
;             for (int ks = 0; ks < 4; ++ks) { ka[ks][0] = *(const LAS bf16x8*)(Kb + kbase[ks]); ka[ks][1] = *(const LAS bf16x8*)(Kb + kbase[ks] + 8192); }
;             __builtin_amdgcn_sched_barrier(0);
; #pragma unroll
;             for (int ks = 0; ks < 4; ++ks) {
;                 s0 = __builtin_amdgcn_mfma_f32_32x32x16_bf16(ka[ks][0], qf[ks], s0, 0, 0, 0);
;                 s1 = __builtin_amdgcn_mfma_f32_32x32x16_bf16(ka[ks][1], qf[ks], s1, 0, 0, 0);
;             }
;             if (kb + 63 > qw0) {
; #pragma unroll
;                 for (int j = 0; j < 16; ++j) { const int key = kb + crow(j, hi); if (key > qrow) s0[j] = -INFINITY; if (key + 32 > qrow) s1[j] = -INFINITY; }
;             }
;             float mxa = max3f(s0[0], s1[0], s0[1]), mxb = max3f(s1[1], s0[2], s1[2]), mxc = max3f(s0[3], s1[3], s0[4]), mxd = max3f(s1[4], s0[5], s1[5]);
;             mxa = max3f(mxa, s0[6], s1[6]); mxb = max3f(mxb, s0[7], s1[7]); mxc = max3f(mxc, s0[8], s1[8]); mxd = max3f(mxd, s0[9], s1[9]);
;             mxa = max3f(mxa, s0[10], s1[10]); mxb = max3f(mxb, s0[11], s1[11]); mxc = max3f(mxc, s0[12], s1[12]); mxd = max3f(mxd, s0[13], s1[13]);
;             mxa = max3f(mxa, s0[14], s1[14]); mxb = max3f(mxb, s0[15], s1[15]);
;             float mx = max3f(mxa, mxb, max3f(mxc, mxd, mxd));
;             { auto rr = __builtin_amdgcn_permlane32_swap(__builtin_bit_cast(unsigned, mx), __builtin_bit_cast(unsigned, mx), false, false);
;               mx = fmaxf(__builtin_bit_cast(float, rr[0]), __builtin_bit_cast(float, rr[1])); }
;             if (__any(mx > mrun + 8.0f)) {
	s_add_i32 m0, s73, 0x4000
	s_nop 0
	global_load_lds_dwordx4 v[134:135], off
	s_add_i32 m0, s73, 0x6000
	s_nop 0
	global_load_lds_dwordx4 v[200:201], off
	s_waitcnt lgkmcnt(7)
	v_mfma_f32_32x32x16_bf16 v[82:97], v[136:139], v[110:113], v[222:237]
	v_add_f32_e32 v122, v66, v67
	v_add_f32_e32 v123, v68, v69
	v_add_f32_e32 v122, v122, v70
	v_add_f32_e32 v123, v123, v71
	s_waitcnt lgkmcnt(5)
	v_mfma_f32_32x32x16_bf16 v[82:97], v[204:207], v[106:109], v[82:97]
	v_add_f32_e32 v122, v122, v72
	v_add_f32_e32 v123, v123, v73
	v_add_f32_e32 v122, v122, v123
	v_add_f32_e32 v167, v167, v122
	s_waitcnt lgkmcnt(3)
	v_mfma_f32_32x32x16_bf16 v[82:97], v[238:241], v[102:105], v[82:97]
	v_add_f32_e32 v122, v74, v75
	v_add_f32_e32 v123, v76, v77
	v_add_f32_e32 v122, v122, v78
	v_add_f32_e32 v123, v123, v79
	s_waitcnt lgkmcnt(1)
	v_mfma_f32_32x32x16_bf16 v[82:97], v[246:249], v[98:101], v[82:97]
	v_add_f32_e32 v122, v122, v80
	v_add_f32_e32 v123, v123, v81
	v_add_f32_e32 v122, v122, v123
	v_add_f32_e32 v167, v167, v122
	s_waitcnt lgkmcnt(0)
	v_mfma_f32_32x32x16_bf16 v[66:81], v[140:143], v[110:113], v[222:237]
	v_mfma_f32_32x32x16_bf16 v[66:81], v[208:211], v[106:109], v[66:81]
	v_mfma_f32_32x32x16_bf16 v[66:81], v[242:245], v[102:105], v[66:81]
	v_mfma_f32_32x32x16_bf16 v[66:81], v[250:253], v[98:101], v[66:81]
	ds_read_b64_tr_b16 v[136:137], v114 offset:32768
	ds_read_b64_tr_b16 v[138:139], v115 offset:32768
	ds_read_b64_tr_b16 v[140:141], v116 offset:32768
	ds_read_b64_tr_b16 v[142:143], v117 offset:32768
	ds_read_b64_tr_b16 v[204:205], v118 offset:32768
	ds_read_b64_tr_b16 v[206:207], v119 offset:32768
	ds_read_b64_tr_b16 v[208:209], v120 offset:32768
	ds_read_b64_tr_b16 v[210:211], v121 offset:32768
	ds_read_b64_tr_b16 v[238:239], v114 offset:36864
	ds_read_b64_tr_b16 v[240:241], v115 offset:36864
	ds_read_b64_tr_b16 v[242:243], v116 offset:36864
	ds_read_b64_tr_b16 v[244:245], v117 offset:36864
	s_nop 1
	v_max3_f32 v122, v82, v66, v83
	v_max3_f32 v123, v67, v84, v68
	v_max3_f32 v124, v85, v69, v86
	v_max3_f32 v125, v70, v87, v71
	v_max3_f32 v122, v122, v88, v72
	v_max3_f32 v123, v123, v89, v73
	v_max3_f32 v124, v124, v90, v74
	v_max3_f32 v125, v125, v91, v75
	v_max3_f32 v122, v122, v92, v76
	v_max3_f32 v123, v123, v93, v77
	v_max3_f32 v124, v124, v94, v78
	v_max3_f32 v125, v125, v95, v79
	v_max3_f32 v122, v122, v96, v80
	v_max3_f32 v123, v123, v97, v81
	v_max3_f32 v122, v122, v123, v124
	v_max_f32_e32 v122, v122, v125
	v_mov_b32_e32 v203, v122
	s_nop 1
	v_permlane32_swap_b32_e32 v122, v203
	s_nop 1
	v_max_f32_e32 v122, v122, v203
	s_mov_b32 s70, 0
	v_cmp_lt_f32_e32 vcc, 0x41000000, v122
	s_cmp_eq_u32 s71, 0
	s_cbranch_scc1 .Lat1_u2_first
	s_cbranch_vccz .Lat1_u2_norescale
	s_branch .Lat1_u2_rescale

; __device__ __forceinline__ unsigned pk2(float lo, float hi) { f32x2 v = {lo, hi}; bf16x2_t b = __builtin_convertvector(v, bf16x2_t); return __builtin_bit_cast(unsigned, b); }
; __device__ __forceinline__ s16x4 vtr(LAS const unsigned char* p) { return __builtin_bit_cast(s16x4, __builtin_amdgcn_ds_read_tr16_b64_v4i16((LAS v4i16_t*)p)); }
; __device__ __forceinline__ bf16x8 cat8(s16x4 a, s16x4 b) { return (bf16x8){a[0], a[1], a[2], a[3], b[0], b[1], b[2], b[3]}; }
; __device__ __forceinline__ void attn_block(LAS unsigned char* lds, const bf16_t* P, bf16_t* mix, int b, int h, int qb, float lam, float outscale, const float* subln) {
;     ...
;             for (int j = 0; j < 16; ++j) { s0[j] = __builtin_amdgcn_exp2f(s0[j] - mrun); s1[j] = __builtin_amdgcn_exp2f(s1[j] - mrun); }
;             float ps0 = 0.f, ps1 = 0.f, ps2 = 0.f, ps3 = 0.f;
; #pragma unroll
;             for (int j = 0; j < 16; j += 2) { ps0 += s0[j]; ps1 += s1[j]; ps2 += s0[j + 1]; ps3 += s1[j + 1]; }
;             lrun += (ps0 + ps1) + (ps2 + ps3);
;             bf16x8 pb[4];
; #pragma unroll
;             for (int s2 = 0; s2 < 2; ++s2) {
;                 u32x4 w0, w1;
;                 w0.x = pk2(s0[8 * s2 + 0], s0[8 * s2 + 1]); w0.y = pk2(s0[8 * s2 + 2], s0[8 * s2 + 3]); w0.z = pk2(s0[8 * s2 + 4], s0[8 * s2 + 5]); w0.w = pk2(s0[8 * s2 + 6], s0[8 * s2 + 7]);
;                 w1.x = pk2(s1[8 * s2 + 0], s1[8 * s2 + 1]); w1.y = pk2(s1[8 * s2 + 2], s1[8 * s2 + 3]); w1.z = pk2(s1[8 * s2 + 4], s1[8 * s2 + 5]); w1.w = pk2(s1[8 * s2 + 6], s1[8 * s2 + 7]);
;                 pb[s2] = __builtin_bit_cast(bf16x8, w0); pb[2 + s2] = __builtin_bit_cast(bf16x8, w1);
;             }
; #pragma unroll
;             for (int s = 0; s < 4; ++s) {
; #pragma unroll
;                 for (int c = 0; c < 4; ++c) {
;                     const s16x4 v0 = vtr(Vb + vbase[c][0] + 4096 * s);
;                     const s16x4 v1 = vtr(Vb + vbase[c][1] + 4096 * s);
;                     o[c] = __builtin_amdgcn_mfma_f32_32x32x16_bf16(cat8(v0, v1), pb[s], o[c], 0, 0, 0);
;                 }
;             }
.Lat1_u2_norescale:
	v_exp_f32_e32 v82, v82
	v_exp_f32_e32 v83, v83
	v_exp_f32_e32 v84, v84
	v_exp_f32_e32 v85, v85
	v_exp_f32_e32 v86, v86
	v_exp_f32_e32 v87, v87
	v_exp_f32_e32 v88, v88
	v_exp_f32_e32 v89, v89
	v_exp_f32_e32 v90, v90
	v_exp_f32_e32 v91, v91
	v_exp_f32_e32 v92, v92
	v_exp_f32_e32 v93, v93
	v_exp_f32_e32 v94, v94
	v_exp_f32_e32 v95, v95
	v_exp_f32_e32 v96, v96
	v_exp_f32_e32 v97, v97
	v_cvt_pk_bf16_f32 v184, v82, v83
	v_cvt_pk_bf16_f32 v185, v84, v85
	v_cvt_pk_bf16_f32 v186, v86, v87
	v_cvt_pk_bf16_f32 v187, v88, v89
	v_cvt_pk_bf16_f32 v188, v90, v91
	v_cvt_pk_bf16_f32 v189, v92, v93
	v_cvt_pk_bf16_f32 v190, v94, v95
	v_cvt_pk_bf16_f32 v191, v96, v97
	v_add_f32_e32 v122, v82, v83
	v_add_f32_e32 v123, v84, v85
	v_add_f32_e32 v122, v122, v86
	v_add_f32_e32 v123, v123, v87
	v_add_f32_e32 v122, v122, v88
	v_add_f32_e32 v123, v123, v89
	v_add_f32_e32 v122, v122, v123
	v_add_f32_e32 v167, v167, v122
	v_add_f32_e32 v124, v90, v91
	v_add_f32_e32 v125, v92, v93
	v_add_f32_e32 v124, v124, v94
	v_add_f32_e32 v125, v125, v95
	v_add_f32_e32 v124, v124, v96
	v_add_f32_e32 v125, v125, v97
	v_add_f32_e32 v124, v124, v125
	v_add_f32_e32 v167, v167, v124
	s_add_i32 m0, s73, 0xb800
	s_nop 0
	global_load_lds_dwordx4 v[134:135], off offset:2048
	s_add_i32 m0, s73, 0xd800
	s_nop 0
	global_load_lds_dwordx4 v[200:201], off offset:2048
	v_lshl_add_u64 v[134:135], v[134:135], 0, s[40:41]
	v_lshl_add_u64 v[200:201], v[200:201], 0, s[40:41]
	s_waitcnt lgkmcnt(8)
	v_mfma_f32_32x32x16_bf16 v[50:65], v[136:139], v[184:187], v[50:65]
	ds_read_b64_tr_b16 v[246:247], v118 offset:36864
	ds_read_b64_tr_b16 v[248:249], v119 offset:36864
	v_exp_f32_e32 v66, v66
	v_exp_f32_e32 v67, v67
	v_exp_f32_e32 v68, v68
	v_mfma_f32_32x32x16_bf16 v[34:49], v[140:143], v[184:187], v[34:49]
	ds_read_b64_tr_b16 v[250:251], v120 offset:36864
	ds_read_b64_tr_b16 v[252:253], v121 offset:36864
	v_exp_f32_e32 v69, v69
	v_exp_f32_e32 v70, v70
	v_exp_f32_e32 v71, v71
	s_waitcnt lgkmcnt(8)
	v_mfma_f32_32x32x16_bf16 v[18:33], v[204:207], v[184:187], v[18:33]
	ds_read_b64_tr_b16 v[136:137], v114 offset:40960
	ds_read_b64_tr_b16 v[138:139], v115 offset:40960
	v_exp_f32_e32 v72, v72
	v_exp_f32_e32 v73, v73
	v_cvt_pk_bf16_f32 v192, v66, v67
	v_mfma_f32_32x32x16_bf16 v[2:17], v[208:211], v[184:187], v[2:17]
	ds_read_b64_tr_b16 v[140:141], v116 offset:40960
	ds_read_b64_tr_b16 v[142:143], v117 offset:40960
	v_cvt_pk_bf16_f32 v193, v68, v69
	v_cvt_pk_bf16_f32 v194, v70, v71
	v_cvt_pk_bf16_f32 v195, v72, v73
	s_waitcnt lgkmcnt(8)
	v_mfma_f32_32x32x16_bf16 v[50:65], v[238:241], v[188:191], v[50:65]
	ds_read_b64_tr_b16 v[204:205], v118 offset:40960
	ds_read_b64_tr_b16 v[206:207], v119 offset:40960
	v_exp_f32_e32 v74, v74
	v_exp_f32_e32 v75, v75
	v_exp_f32_e32 v76, v76
	v_mfma_f32_32x32x16_bf16 v[34:49], v[242:245], v[188:191], v[34:49]
	ds_read_b64_tr_b16 v[208:209], v120 offset:40960
	ds_read_b64_tr_b16 v[210:211], v121 offset:40960
	v_exp_f32_e32 v77, v77
	v_exp_f32_e32 v78, v78
	v_exp_f32_e32 v79, v79
	s_waitcnt lgkmcnt(8)
	v_mfma_f32_32x32x16_bf16 v[18:33], v[246:249], v[188:191], v[18:33]
	ds_read_b64_tr_b16 v[238:239], v114 offset:45056
	ds_read_b64_tr_b16 v[240:241], v115 offset:45056
	v_exp_f32_e32 v80, v80
	v_exp_f32_e32 v81, v81
	v_cvt_pk_bf16_f32 v196, v74, v75
	v_mfma_f32_32x32x16_bf16 v[2:17], v[250:253], v[188:191], v[2:17]
	ds_read_b64_tr_b16 v[242:243], v116 offset:45056
	ds_read_b64_tr_b16 v[244:245], v117 offset:45056
	v_cvt_pk_bf16_f32 v197, v76, v77
	v_cvt_pk_bf16_f32 v198, v78, v79
	v_cvt_pk_bf16_f32 v199, v80, v81
	s_waitcnt lgkmcnt(8)
	v_mfma_f32_32x32x16_bf16 v[50:65], v[136:139], v[192:195], v[50:65]
	ds_read_b64_tr_b16 v[246:247], v118 offset:45056
	ds_read_b64_tr_b16 v[248:249], v119 offset:45056
	v_mfma_f32_32x32x16_bf16 v[34:49], v[140:143], v[192:195], v[34:49]
	ds_read_b64_tr_b16 v[250:251], v120 offset:45056
	ds_read_b64_tr_b16 v[252:253], v121 offset:45056
	s_waitcnt lgkmcnt(8)
	v_mfma_f32_32x32x16_bf16 v[18:33], v[204:207], v[192:195], v[18:33]
	v_mfma_f32_32x32x16_bf16 v[2:17], v[208:211], v[192:195], v[2:17]
	s_waitcnt lgkmcnt(4)
	v_mfma_f32_32x32x16_bf16 v[50:65], v[238:241], v[196:199], v[50:65]
	v_mfma_f32_32x32x16_bf16 v[34:49], v[242:245], v[196:199], v[34:49]
	s_waitcnt lgkmcnt(0)
	v_mfma_f32_32x32x16_bf16 v[18:33], v[246:249], v[196:199], v[18:33]
	v_mfma_f32_32x32x16_bf16 v[2:17], v[250:253], v[196:199], v[2:17]
	ds_read_b128 v[136:139], v126 offset:16384
	ds_read_b128 v[140:143], v126 offset:24576
	ds_read_b128 v[204:207], v127 offset:16384
	ds_read_b128 v[208:211], v127 offset:24576
	ds_read_b128 v[238:241], v128 offset:16384
	ds_read_b128 v[242:245], v128 offset:24576
	ds_read_b128 v[246:249], v129 offset:16384
	ds_read_b128 v[250:253], v129 offset:24576
	s_waitcnt vmcnt(6)
	s_add_i32 s71, s71, 64
	s_barrier
; #define LAS __attribute__((address_space(3)))
; __device__ __forceinline__ float max3f(float a, float b, float c) { float r; asm("v_max3_f32 %0, %1, %2, %3" : "=v"(r) : "v"(a), "v"(b), "v"(c)); return r; }
; __device__ __forceinline__ int crow(int r, int hi) { return (r & 3) + 8 * (r >> 2) + 4 * hi; }
; __device__ __forceinline__ void attn_block(LAS unsigned char* lds, const bf16_t* P, bf16_t* mix, int b, int h, int qb, float lam, float outscale, const float* subln) {
;     ...
;             f32x16 s0, s1;
; #pragma unroll
;             for (int j = 0; j < 16; ++j) { s0[j] = 0.f; s1[j] = 0.f; }
;             bf16x8 ka[4][2];
; #pragma unroll
;             for (int ks = 0; ks < 4; ++ks) { ka[ks][0] = *(const LAS bf16x8*)(Kb + kbase[ks]); ka[ks][1] = *(const LAS bf16x8*)(Kb + kbase[ks] + 8192); }
;             __builtin_amdgcn_sched_barrier(0);
; #pragma unroll
;             for (int ks = 0; ks < 4; ++ks) {
;                 s0 = __builtin_amdgcn_mfma_f32_32x32x16_bf16(ka[ks][0], qf[ks], s0, 0, 0, 0);
;                 s1 = __builtin_amdgcn_mfma_f32_32x32x16_bf16(ka[ks][1], qf[ks], s1, 0, 0, 0);
;             }
;             if (kb + 63 > qw0) {
; #pragma unroll
;                 for (int j = 0; j < 16; ++j) { const int key = kb + crow(j, hi); if (key > qrow) s0[j] = -INFINITY; if (key + 32 > qrow) s1[j] = -INFINITY; }
;             }
;             float mxa = max3f(s0[0], s1[0], s0[1]), mxb = max3f(s1[1], s0[2], s1[2]), mxc = max3f(s0[3], s1[3], s0[4]), mxd = max3f(s1[4], s0[5], s1[5]);
;             mxa = max3f(mxa, s0[6], s1[6]); mxb = max3f(mxb, s0[7], s1[7]); mxc = max3f(mxc, s0[8], s1[8]); mxd = max3f(mxd, s0[9], s1[9]);
;             mxa = max3f(mxa, s0[10], s1[10]); mxb = max3f(mxb, s0[11], s1[11]); mxc = max3f(mxc, s0[12], s1[12]); mxd = max3f(mxd, s0[13], s1[13]);
;             mxa = max3f(mxa, s0[14], s1[14]); mxb = max3f(mxb, s0[15], s1[15]);
;             float mx = max3f(mxa, mxb, max3f(mxc, mxd, mxd));
;             { auto rr = __builtin_amdgcn_permlane32_swap(__builtin_bit_cast(unsigned, mx), __builtin_bit_cast(unsigned, mx), false, false);
;               mx = fmaxf(__builtin_bit_cast(float, rr[0]), __builtin_bit_cast(float, rr[1])); }
;             if (__any(mx > mrun + 8.0f)) {
	s_add_i32 m0, s73, 0x10000
	s_nop 0
	global_load_lds_dwordx4 v[134:135], off
	s_add_i32 m0, s73, 0x12000
	s_nop 0
	global_load_lds_dwordx4 v[200:201], off
	s_waitcnt lgkmcnt(7)
	v_mfma_f32_32x32x16_bf16 v[82:97], v[136:139], v[110:113], v[222:237]
	v_add_f32_e32 v122, v66, v67
	v_add_f32_e32 v123, v68, v69
	v_add_f32_e32 v122, v122, v70
	v_add_f32_e32 v123, v123, v71
	s_waitcnt lgkmcnt(5)
	v_mfma_f32_32x32x16_bf16 v[82:97], v[204:207], v[106:109], v[82:97]
	v_add_f32_e32 v122, v122, v72
	v_add_f32_e32 v123, v123, v73
	v_add_f32_e32 v122, v122, v123
	v_add_f32_e32 v167, v167, v122
	s_waitcnt lgkmcnt(3)
	v_mfma_f32_32x32x16_bf16 v[82:97], v[238:241], v[102:105], v[82:97]
	v_add_f32_e32 v122, v74, v75
	v_add_f32_e32 v123, v76, v77
	v_add_f32_e32 v122, v122, v78
	v_add_f32_e32 v123, v123, v79
	s_waitcnt lgkmcnt(1)
	v_mfma_f32_32x32x16_bf16 v[82:97], v[246:249], v[98:101], v[82:97]
	v_add_f32_e32 v122, v122, v80
	v_add_f32_e32 v123, v123, v81
	v_add_f32_e32 v122, v122, v123
	v_add_f32_e32 v167, v167, v122
	s_waitcnt lgkmcnt(0)
	v_mfma_f32_32x32x16_bf16 v[66:81], v[140:143], v[110:113], v[222:237]
	v_mfma_f32_32x32x16_bf16 v[66:81], v[208:211], v[106:109], v[66:81]
	v_mfma_f32_32x32x16_bf16 v[66:81], v[242:245], v[102:105], v[66:81]
	v_mfma_f32_32x32x16_bf16 v[66:81], v[250:253], v[98:101], v[66:81]
	ds_read_b64_tr_b16 v[136:137], v114 offset:49152
	ds_read_b64_tr_b16 v[138:139], v115 offset:49152
	ds_read_b64_tr_b16 v[140:141], v116 offset:49152
	ds_read_b64_tr_b16 v[142:143], v117 offset:49152
	ds_read_b64_tr_b16 v[204:205], v118 offset:49152
	ds_read_b64_tr_b16 v[206:207], v119 offset:49152
	ds_read_b64_tr_b16 v[208:209], v120 offset:49152
	ds_read_b64_tr_b16 v[210:211], v121 offset:49152
	ds_read_b64_tr_b16 v[238:239], v114 offset:53248
	ds_read_b64_tr_b16 v[240:241], v115 offset:53248
	ds_read_b64_tr_b16 v[242:243], v116 offset:53248
	ds_read_b64_tr_b16 v[244:245], v117 offset:53248
	s_nop 1
	v_max3_f32 v122, v82, v66, v83
	v_max3_f32 v123, v67, v84, v68
	v_max3_f32 v124, v85, v69, v86
	v_max3_f32 v125, v70, v87, v71
	v_max3_f32 v122, v122, v88, v72
	v_max3_f32 v123, v123, v89, v73
	v_max3_f32 v124, v124, v90, v74
	v_max3_f32 v125, v125, v91, v75
	v_max3_f32 v122, v122, v92, v76
	v_max3_f32 v123, v123, v93, v77
	v_max3_f32 v124, v124, v94, v78
	v_max3_f32 v125, v125, v95, v79
	v_max3_f32 v122, v122, v96, v80
	v_max3_f32 v123, v123, v97, v81
	v_max3_f32 v122, v122, v123, v124
	v_max_f32_e32 v122, v122, v125
	v_mov_b32_e32 v203, v122
	s_nop 1
	v_permlane32_swap_b32_e32 v122, v203
	s_nop 1
	v_max_f32_e32 v122, v122, v203
	s_mov_b32 s70, 0
	v_cmp_lt_f32_e32 vcc, 0x41000000, v122
	s_cmp_eq_u32 s71, 0
	s_cbranch_scc1 .Lat1_u3_first
	s_cbranch_vccz .Lat1_u3_norescale
	s_branch .Lat1_u3_rescale

; #define LAS __attribute__((address_space(3)))
; __device__ __forceinline__ unsigned pk2(float lo, float hi) { f32x2 v = {lo, hi}; bf16x2_t b = __builtin_convertvector(v, bf16x2_t); return __builtin_bit_cast(unsigned, b); }
; __device__ __forceinline__ s16x4 vtr(LAS const unsigned char* p) { return __builtin_bit_cast(s16x4, __builtin_amdgcn_ds_read_tr16_b64_v4i16((LAS v4i16_t*)p)); }
; __device__ __forceinline__ void attn_block(LAS unsigned char* lds, const bf16_t* P, bf16_t* mix, int b, int h, int qb, float lam, float outscale, const float* subln) {
;     ...
;             for (int j = 0; j < 16; ++j) { s0[j] = __builtin_amdgcn_exp2f(s0[j] - mrun); s1[j] = __builtin_amdgcn_exp2f(s1[j] - mrun); }
;             float ps0 = 0.f, ps1 = 0.f, ps2 = 0.f, ps3 = 0.f;
; #pragma unroll
;             for (int j = 0; j < 16; j += 2) { ps0 += s0[j]; ps1 += s1[j]; ps2 += s0[j + 1]; ps3 += s1[j + 1]; }
;             lrun += (ps0 + ps1) + (ps2 + ps3);
;             bf16x8 pb[4];
; #pragma unroll
;             for (int s2 = 0; s2 < 2; ++s2) {
;                 u32x4 w0, w1;
;                 w0.x = pk2(s0[8 * s2 + 0], s0[8 * s2 + 1]); w0.y = pk2(s0[8 * s2 + 2], s0[8 * s2 + 3]); w0.z = pk2(s0[8 * s2 + 4], s0[8 * s2 + 5]); w0.w = pk2(s0[8 * s2 + 6], s0[8 * s2 + 7]);
;                 w1.x = pk2(s1[8 * s2 + 0], s1[8 * s2 + 1]); w1.y = pk2(s1[8 * s2 + 2], s1[8 * s2 + 3]); w1.z = pk2(s1[8 * s2 + 4], s1[8 * s2 + 5]); w1.w = pk2(s1[8 * s2 + 6], s1[8 * s2 + 7]);
;                 pb[s2] = __builtin_bit_cast(bf16x8, w0); pb[2 + s2] = __builtin_bit_cast(bf16x8, w1);
;             }
; #pragma unroll
;             for (int s = 0; s < 4; ++s) {
; #pragma unroll
;                 for (int c = 0; c < 4; ++c) {
;                     const s16x4 v0 = vtr(Vb + vbase[c][0] + 4096 * s);
;                     const s16x4 v1 = vtr(Vb + vbase[c][1] + 4096 * s);
;                     o[c] = __builtin_amdgcn_mfma_f32_32x32x16_bf16(cat8(v0, v1), pb[s], o[c], 0, 0, 0);
;                 }
;             }
;         }
;         if (kt + 1 < ntiles) {
;             const int nb = (kt + 1) & 1;
;             *(LAS u32x4*)(lds + ATT_K0 + nb * 16384 + so0) = kr0; *(LAS u32x4*)(lds + ATT_K0 + nb * 16384 + so1) = kr1;
;             *(LAS u32x4*)(lds + ATT_V0 + nb * 16384 + so0) = vr0; *(LAS u32x4*)(lds + ATT_V0 + nb * 16384 + so1) = vr1;
;         }
;     }
.Lat1_u3_norescale:
	v_exp_f32_e32 v82, v82
	v_exp_f32_e32 v83, v83
	v_exp_f32_e32 v84, v84
	v_exp_f32_e32 v85, v85
	v_exp_f32_e32 v86, v86
	v_exp_f32_e32 v87, v87
	v_exp_f32_e32 v88, v88
	v_exp_f32_e32 v89, v89
	v_exp_f32_e32 v90, v90
	v_exp_f32_e32 v91, v91
	v_exp_f32_e32 v92, v92
	v_exp_f32_e32 v93, v93
	v_exp_f32_e32 v94, v94
	v_exp_f32_e32 v95, v95
	v_exp_f32_e32 v96, v96
	v_exp_f32_e32 v97, v97
	v_cvt_pk_bf16_f32 v184, v82, v83
	v_cvt_pk_bf16_f32 v185, v84, v85
	v_cvt_pk_bf16_f32 v186, v86, v87
	v_cvt_pk_bf16_f32 v187, v88, v89
	v_cvt_pk_bf16_f32 v188, v90, v91
	v_cvt_pk_bf16_f32 v189, v92, v93
	v_cvt_pk_bf16_f32 v190, v94, v95
	v_cvt_pk_bf16_f32 v191, v96, v97
	v_add_f32_e32 v122, v82, v83
	v_add_f32_e32 v123, v84, v85
	v_add_f32_e32 v122, v122, v86
	v_add_f32_e32 v123, v123, v87
	v_add_f32_e32 v122, v122, v88
	v_add_f32_e32 v123, v123, v89
	v_add_f32_e32 v122, v122, v123
	v_add_f32_e32 v167, v167, v122
	v_add_f32_e32 v124, v90, v91
	v_add_f32_e32 v125, v92, v93
	v_add_f32_e32 v124, v124, v94
	v_add_f32_e32 v125, v125, v95
	v_add_f32_e32 v124, v124, v96
	v_add_f32_e32 v125, v125, v97
	v_add_f32_e32 v124, v124, v125
	v_add_f32_e32 v167, v167, v124
	s_add_i32 m0, s73, 0x17800
	s_nop 0
	global_load_lds_dwordx4 v[134:135], off offset:2048
	s_add_i32 m0, s73, 0x19800
	s_nop 0
	global_load_lds_dwordx4 v[200:201], off offset:2048
	v_lshl_add_u64 v[134:135], v[134:135], 0, s[40:41]
	v_lshl_add_u64 v[200:201], v[200:201], 0, s[40:41]
	s_waitcnt lgkmcnt(8)
	v_mfma_f32_32x32x16_bf16 v[50:65], v[136:139], v[184:187], v[50:65]
	ds_read_b64_tr_b16 v[246:247], v118 offset:53248
	ds_read_b64_tr_b16 v[248:249], v119 offset:53248
	v_exp_f32_e32 v66, v66
	v_exp_f32_e32 v67, v67
	v_exp_f32_e32 v68, v68
	v_mfma_f32_32x32x16_bf16 v[34:49], v[140:143], v[184:187], v[34:49]
	ds_read_b64_tr_b16 v[250:251], v120 offset:53248
	ds_read_b64_tr_b16 v[252:253], v121 offset:53248
	v_exp_f32_e32 v69, v69
	v_exp_f32_e32 v70, v70
	v_exp_f32_e32 v71, v71
	s_waitcnt lgkmcnt(8)
	v_mfma_f32_32x32x16_bf16 v[18:33], v[204:207], v[184:187], v[18:33]
	ds_read_b64_tr_b16 v[136:137], v114 offset:57344
	ds_read_b64_tr_b16 v[138:139], v115 offset:57344
	v_exp_f32_e32 v72, v72
	v_exp_f32_e32 v73, v73
	v_cvt_pk_bf16_f32 v192, v66, v67
	v_mfma_f32_32x32x16_bf16 v[2:17], v[208:211], v[184:187], v[2:17]
	ds_read_b64_tr_b16 v[140:141], v116 offset:57344
	ds_read_b64_tr_b16 v[142:143], v117 offset:57344
	v_cvt_pk_bf16_f32 v193, v68, v69
	v_cvt_pk_bf16_f32 v194, v70, v71
	v_cvt_pk_bf16_f32 v195, v72, v73
	s_waitcnt lgkmcnt(8)
	v_mfma_f32_32x32x16_bf16 v[50:65], v[238:241], v[188:191], v[50:65]
	ds_read_b64_tr_b16 v[204:205], v118 offset:57344
	ds_read_b64_tr_b16 v[206:207], v119 offset:57344
	v_exp_f32_e32 v74, v74
	v_exp_f32_e32 v75, v75
	v_exp_f32_e32 v76, v76
	v_mfma_f32_32x32x16_bf16 v[34:49], v[242:245], v[188:191], v[34:49]
	ds_read_b64_tr_b16 v[208:209], v120 offset:57344
	ds_read_b64_tr_b16 v[210:211], v121 offset:57344
	v_exp_f32_e32 v77, v77
	v_exp_f32_e32 v78, v78
	v_exp_f32_e32 v79, v79
	s_waitcnt lgkmcnt(8)
	v_mfma_f32_32x32x16_bf16 v[18:33], v[246:249], v[188:191], v[18:33]
	ds_read_b64_tr_b16 v[238:239], v114 offset:61440
	ds_read_b64_tr_b16 v[240:241], v115 offset:61440
	v_exp_f32_e32 v80, v80
	v_exp_f32_e32 v81, v81
	v_cvt_pk_bf16_f32 v196, v74, v75
	v_mfma_f32_32x32x16_bf16 v[2:17], v[250:253], v[188:191], v[2:17]
	ds_read_b64_tr_b16 v[242:243], v116 offset:61440
	ds_read_b64_tr_b16 v[244:245], v117 offset:61440
	v_cvt_pk_bf16_f32 v197, v76, v77
	v_cvt_pk_bf16_f32 v198, v78, v79
	v_cvt_pk_bf16_f32 v199, v80, v81
	s_waitcnt lgkmcnt(8)
	v_mfma_f32_32x32x16_bf16 v[50:65], v[136:139], v[192:195], v[50:65]
	ds_read_b64_tr_b16 v[246:247], v118 offset:61440
	ds_read_b64_tr_b16 v[248:249], v119 offset:61440
	v_mfma_f32_32x32x16_bf16 v[34:49], v[140:143], v[192:195], v[34:49]
	ds_read_b64_tr_b16 v[250:251], v120 offset:61440
	ds_read_b64_tr_b16 v[252:253], v121 offset:61440
	s_waitcnt lgkmcnt(8)
	v_mfma_f32_32x32x16_bf16 v[18:33], v[204:207], v[192:195], v[18:33]
	v_mfma_f32_32x32x16_bf16 v[2:17], v[208:211], v[192:195], v[2:17]
	s_waitcnt lgkmcnt(4)
	v_mfma_f32_32x32x16_bf16 v[50:65], v[238:241], v[196:199], v[50:65]
	v_mfma_f32_32x32x16_bf16 v[34:49], v[242:245], v[196:199], v[34:49]
	s_waitcnt lgkmcnt(0)
	v_mfma_f32_32x32x16_bf16 v[18:33], v[246:249], v[196:199], v[18:33]
	v_mfma_f32_32x32x16_bf16 v[2:17], v[250:253], v[196:199], v[2:17]
	ds_read_b128 v[136:139], v180 offset:0
	ds_read_b128 v[140:143], v180 offset:8192
	ds_read_b128 v[204:207], v181 offset:0
	ds_read_b128 v[208:211], v181 offset:8192
	ds_read_b128 v[238:241], v178 offset:0
	ds_read_b128 v[242:245], v178 offset:8192
	ds_read_b128 v[246:249], v177 offset:0
	ds_read_b128 v[250:253], v177 offset:8192
	s_waitcnt vmcnt(6)
	s_add_i32 s71, s71, 64
	s_add_i32 s72, s71, 384
	s_cmp_le_u32 s72, s36
	s_barrier
	s_cbranch_scc1 .Lat1_U_top
	v_add_f32_e32 v122, v66, v67
	v_add_f32_e32 v123, v68, v69
	v_add_f32_e32 v122, v122, v70
	v_add_f32_e32 v123, v123, v71
	v_add_f32_e32 v122, v122, v72
	v_add_f32_e32 v123, v123, v73
	v_add_f32_e32 v122, v122, v123
	v_add_f32_e32 v167, v167, v122
	v_add_f32_e32 v122, v74, v75
	v_add_f32_e32 v123, v76, v77
	v_add_f32_e32 v122, v122, v78
	v_add_f32_e32 v123, v123, v79
	v_add_f32_e32 v122, v122, v80
	v_add_f32_e32 v123, v123, v81
	v_add_f32_e32 v122, v122, v123
	v_add_f32_e32 v167, v167, v122

; #define LAS __attribute__((address_space(3)))
; __device__ __forceinline__ float max3f(float a, float b, float c) { float r; asm("v_max3_f32 %0, %1, %2, %3" : "=v"(r) : "v"(a), "v"(b), "v"(c)); return r; }
; __device__ __forceinline__ void attn_block(LAS unsigned char* lds, const bf16_t* P, bf16_t* mix, int b, int h, int qb, float lam, float outscale, const float* subln) {
;     ...
;         const int kb = 64 * kt;
;         if (kb <= qw0 + 31) {
;             LAS const unsigned char* Kb = lds + ATT_K0 + buf * 16384;
;             LAS const unsigned char* Vb = lds + ATT_V0 + buf * 16384;
;             f32x16 s0, s1;
; #pragma unroll
;             for (int j = 0; j < 16; ++j) { s0[j] = 0.f; s1[j] = 0.f; }
;             bf16x8 ka[4][2];
; #pragma unroll
;             for (int ks = 0; ks < 4; ++ks) { ka[ks][0] = *(const LAS bf16x8*)(Kb + kbase[ks]); ka[ks][1] = *(const LAS bf16x8*)(Kb + kbase[ks] + 8192); }
;             __builtin_amdgcn_sched_barrier(0);
; #pragma unroll
;             for (int ks = 0; ks < 4; ++ks) {
;                 s0 = __builtin_amdgcn_mfma_f32_32x32x16_bf16(ka[ks][0], qf[ks], s0, 0, 0, 0);
;                 s1 = __builtin_amdgcn_mfma_f32_32x32x16_bf16(ka[ks][1], qf[ks], s1, 0, 0, 0);
;             }
;             if (kb + 63 > qw0) {
; #pragma unroll
;                 for (int j = 0; j < 16; ++j) { const int key = kb + crow(j, hi); if (key > qrow) s0[j] = -INFINITY; if (key + 32 > qrow) s1[j] = -INFINITY; }
;             }
;             float mxa = max3f(s0[0], s1[0], s0[1]), mxb = max3f(s1[1], s0[2], s1[2]), mxc = max3f(s0[3], s1[3], s0[4]), mxd = max3f(s1[4], s0[5], s1[5]);
;             mxa = max3f(mxa, s0[6], s1[6]); mxb = max3f(mxb, s0[7], s1[7]); mxc = max3f(mxc, s0[8], s1[8]); mxd = max3f(mxd, s0[9], s1[9]);
;             mxa = max3f(mxa, s0[10], s1[10]); mxb = max3f(mxb, s0[11], s1[11]); mxc = max3f(mxc, s0[12], s1[12]); mxd = max3f(mxd, s0[13], s1[13]);
;             mxa = max3f(mxa, s0[14], s1[14]); mxb = max3f(mxb, s0[15], s1[15]);
;             float mx = max3f(mxa, mxb, max3f(mxc, mxd, mxd));
;             { auto rr = __builtin_amdgcn_permlane32_swap(__builtin_bit_cast(unsigned, mx), __builtin_bit_cast(unsigned, mx), false, false);
;               mx = fmaxf(__builtin_bit_cast(float, rr[0]), __builtin_bit_cast(float, rr[1])); }
;             if (__any(mx > mrun + 8.0f)) {
.Lat2_pre_done:
	s_waitcnt lgkmcnt(0)
	s_barrier
	ds_read_b128 v[136:139], v178
	ds_read_b128 v[140:143], v178 offset:8192
	ds_read_b128 v[204:207], v181
	ds_read_b128 v[208:211], v181 offset:8192
	ds_read_b128 v[238:241], v180
	ds_read_b128 v[242:245], v180 offset:8192
	ds_read_b128 v[246:249], v179
	ds_read_b128 v[250:253], v179 offset:8192
	s_add_i32 s62, s50, 384
	s_cmp_le_u32 s62, s2
	s_cbranch_scc0 .Lat2_U_none
	v_add_u32_e32 v114, 0x10000, v168
	v_add_u32_e32 v115, 0x10000, v175
	v_add_u32_e32 v116, 0x10000, v172
	v_add_u32_e32 v117, 0x10000, v174
	v_add_u32_e32 v118, 0x10000, v170
	v_add_u32_e32 v119, 0x10000, v173
	v_add_u32_e32 v120, 0x10000, v169
	v_add_u32_e32 v121, 0x10000, v171
	v_add_u32_e32 v126, 0x10000, v178
	v_add_u32_e32 v127, 0x10000, v181
	v_add_u32_e32 v128, 0x10000, v180
	v_add_u32_e32 v129, 0x10000, v179
	s_lshl_b32 s39, s33, 4
	s_and_b32 s39, s39, 0x1c00
	s_mov_b32 s62, s39
	v_mov_b32_e32 v66, 0
	v_mov_b32_e32 v67, 0
	v_mov_b32_e32 v68, 0
	v_mov_b32_e32 v69, 0
	v_mov_b32_e32 v70, 0
	v_mov_b32_e32 v71, 0
	v_mov_b32_e32 v72, 0
	v_mov_b32_e32 v73, 0
	v_mov_b32_e32 v74, 0
	v_mov_b32_e32 v75, 0
	v_mov_b32_e32 v76, 0
	v_mov_b32_e32 v77, 0
	v_mov_b32_e32 v78, 0
	v_mov_b32_e32 v79, 0
	v_mov_b32_e32 v80, 0
	v_mov_b32_e32 v81, 0
.Lat2_U_top:
	s_add_i32 m0, s62, 0x14000
	s_nop 0
	global_load_lds_dwordx4 v[134:135], off
	s_add_i32 m0, s62, 0x16000
	s_nop 0
	global_load_lds_dwordx4 v[200:201], off
	s_waitcnt lgkmcnt(7)
	v_mfma_f32_32x32x16_bf16 v[82:97], v[136:139], v[110:113], v[222:237]
	v_add_f32_e32 v122, v66, v67
	v_add_f32_e32 v123, v68, v69
	v_add_f32_e32 v122, v122, v70
	v_add_f32_e32 v123, v123, v71
	s_waitcnt lgkmcnt(5)
	v_mfma_f32_32x32x16_bf16 v[82:97], v[204:207], v[106:109], v[82:97]
	v_add_f32_e32 v122, v122, v72
	v_add_f32_e32 v123, v123, v73
	v_add_f32_e32 v122, v122, v123
	v_add_f32_e32 v167, v167, v122
	s_waitcnt lgkmcnt(3)
	v_mfma_f32_32x32x16_bf16 v[82:97], v[238:241], v[102:105], v[82:97]
	v_add_f32_e32 v122, v74, v75
	v_add_f32_e32 v123, v76, v77
	v_add_f32_e32 v122, v122, v78
	v_add_f32_e32 v123, v123, v79
	s_waitcnt lgkmcnt(1)
	v_mfma_f32_32x32x16_bf16 v[82:97], v[246:249], v[98:101], v[82:97]
	v_add_f32_e32 v122, v122, v80
	v_add_f32_e32 v123, v123, v81
	v_add_f32_e32 v122, v122, v123
	v_add_f32_e32 v167, v167, v122
	s_waitcnt lgkmcnt(0)
	v_mfma_f32_32x32x16_bf16 v[66:81], v[140:143], v[110:113], v[222:237]
	v_mfma_f32_32x32x16_bf16 v[66:81], v[208:211], v[106:109], v[66:81]
	v_mfma_f32_32x32x16_bf16 v[66:81], v[242:245], v[102:105], v[66:81]
	v_mfma_f32_32x32x16_bf16 v[66:81], v[250:253], v[98:101], v[66:81]
	ds_read_b64_tr_b16 v[136:137], v168 offset:32768
	ds_read_b64_tr_b16 v[138:139], v175 offset:32768
	ds_read_b64_tr_b16 v[140:141], v172 offset:32768
	ds_read_b64_tr_b16 v[142:143], v174 offset:32768
	ds_read_b64_tr_b16 v[204:205], v170 offset:32768
	ds_read_b64_tr_b16 v[206:207], v173 offset:32768
	ds_read_b64_tr_b16 v[208:209], v169 offset:32768
	ds_read_b64_tr_b16 v[210:211], v171 offset:32768
	ds_read_b64_tr_b16 v[238:239], v168 offset:36864
	ds_read_b64_tr_b16 v[240:241], v175 offset:36864
	ds_read_b64_tr_b16 v[242:243], v172 offset:36864
	ds_read_b64_tr_b16 v[244:245], v174 offset:36864
	s_nop 1
	v_max3_f32 v122, v82, v66, v83
	v_max3_f32 v123, v67, v84, v68
	v_max3_f32 v124, v85, v69, v86
	v_max3_f32 v125, v70, v87, v71
	v_max3_f32 v122, v122, v88, v72
	v_max3_f32 v123, v123, v89, v73
	v_max3_f32 v124, v124, v90, v74
	v_max3_f32 v125, v125, v91, v75
	v_max3_f32 v122, v122, v92, v76
	v_max3_f32 v123, v123, v93, v77
	v_max3_f32 v124, v124, v94, v78
	v_max3_f32 v125, v125, v95, v79
	v_max3_f32 v122, v122, v96, v80
	v_max3_f32 v123, v123, v97, v81
	v_max3_f32 v122, v122, v123, v124
	v_max_f32_e32 v122, v122, v125
	v_mov_b32_e32 v203, v122
	s_nop 1
	v_permlane32_swap_b32_e32 v122, v203
	s_nop 1
	v_max_f32_e32 v122, v122, v203
	s_mov_b32 s39, 0
	v_cmp_lt_f32_e32 vcc, 0x41000000, v122
	s_cmp_eq_u32 s50, 0
	s_cbranch_scc1 .Lat2_u0_first
	s_cbranch_vccz .Lat2_u0_norescale
	s_branch .Lat2_u0_rescale

; __device__ __forceinline__ unsigned pk2(float lo, float hi) { f32x2 v = {lo, hi}; bf16x2_t b = __builtin_convertvector(v, bf16x2_t); return __builtin_bit_cast(unsigned, b); }
; __device__ __forceinline__ s16x4 vtr(LAS const unsigned char* p) { return __builtin_bit_cast(s16x4, __builtin_amdgcn_ds_read_tr16_b64_v4i16((LAS v4i16_t*)p)); }
; __device__ __forceinline__ bf16x8 cat8(s16x4 a, s16x4 b) { return (bf16x8){a[0], a[1], a[2], a[3], b[0], b[1], b[2], b[3]}; }
; __device__ __forceinline__ void attn_block(LAS unsigned char* lds, const bf16_t* P, bf16_t* mix, int b, int h, int qb, float lam, float outscale, const float* subln) {
;     ...
;             for (int j = 0; j < 16; ++j) { s0[j] = __builtin_amdgcn_exp2f(s0[j] - mrun); s1[j] = __builtin_amdgcn_exp2f(s1[j] - mrun); }
;             float ps0 = 0.f, ps1 = 0.f, ps2 = 0.f, ps3 = 0.f;
; #pragma unroll
;             for (int j = 0; j < 16; j += 2) { ps0 += s0[j]; ps1 += s1[j]; ps2 += s0[j + 1]; ps3 += s1[j + 1]; }
;             lrun += (ps0 + ps1) + (ps2 + ps3);
;             bf16x8 pb[4];
; #pragma unroll
;             for (int s2 = 0; s2 < 2; ++s2) {
;                 u32x4 w0, w1;
;                 w0.x = pk2(s0[8 * s2 + 0], s0[8 * s2 + 1]); w0.y = pk2(s0[8 * s2 + 2], s0[8 * s2 + 3]); w0.z = pk2(s0[8 * s2 + 4], s0[8 * s2 + 5]); w0.w = pk2(s0[8 * s2 + 6], s0[8 * s2 + 7]);
;                 w1.x = pk2(s1[8 * s2 + 0], s1[8 * s2 + 1]); w1.y = pk2(s1[8 * s2 + 2], s1[8 * s2 + 3]); w1.z = pk2(s1[8 * s2 + 4], s1[8 * s2 + 5]); w1.w = pk2(s1[8 * s2 + 6], s1[8 * s2 + 7]);
;                 pb[s2] = __builtin_bit_cast(bf16x8, w0); pb[2 + s2] = __builtin_bit_cast(bf16x8, w1);
;             }
; #pragma unroll
;             for (int s = 0; s < 4; ++s) {
; #pragma unroll
;                 for (int c = 0; c < 4; ++c) {
;                     const s16x4 v0 = vtr(Vb + vbase[c][0] + 4096 * s);
;                     const s16x4 v1 = vtr(Vb + vbase[c][1] + 4096 * s);
;                     o[c] = __builtin_amdgcn_mfma_f32_32x32x16_bf16(cat8(v0, v1), pb[s], o[c], 0, 0, 0);
;                 }
;             }
.Lat2_u0_norescale:
	v_exp_f32_e32 v82, v82
	v_exp_f32_e32 v83, v83
	v_exp_f32_e32 v84, v84
	v_exp_f32_e32 v85, v85
	v_exp_f32_e32 v86, v86
	v_exp_f32_e32 v87, v87
	v_exp_f32_e32 v88, v88
	v_exp_f32_e32 v89, v89
	v_exp_f32_e32 v90, v90
	v_exp_f32_e32 v91, v91
	v_exp_f32_e32 v92, v92
	v_exp_f32_e32 v93, v93
	v_exp_f32_e32 v94, v94
	v_exp_f32_e32 v95, v95
	v_exp_f32_e32 v96, v96
	v_exp_f32_e32 v97, v97
	v_cvt_pk_bf16_f32 v184, v82, v83
	v_cvt_pk_bf16_f32 v185, v84, v85
	v_cvt_pk_bf16_f32 v186, v86, v87
	v_cvt_pk_bf16_f32 v187, v88, v89
	v_cvt_pk_bf16_f32 v188, v90, v91
	v_cvt_pk_bf16_f32 v189, v92, v93
	v_cvt_pk_bf16_f32 v190, v94, v95
	v_cvt_pk_bf16_f32 v191, v96, v97
	v_add_f32_e32 v122, v82, v83
	v_add_f32_e32 v123, v84, v85
	v_add_f32_e32 v122, v122, v86
	v_add_f32_e32 v123, v123, v87
	v_add_f32_e32 v122, v122, v88
	v_add_f32_e32 v123, v123, v89
	v_add_f32_e32 v122, v122, v123
	v_add_f32_e32 v167, v167, v122
	v_add_f32_e32 v124, v90, v91
	v_add_f32_e32 v125, v92, v93
	v_add_f32_e32 v124, v124, v94
	v_add_f32_e32 v125, v125, v95
	v_add_f32_e32 v124, v124, v96
	v_add_f32_e32 v125, v125, v97
	v_add_f32_e32 v124, v124, v125
	v_add_f32_e32 v167, v167, v124
	s_add_i32 m0, s62, 0x1b800
	s_nop 0
	global_load_lds_dwordx4 v[134:135], off offset:2048
	s_add_i32 m0, s62, 0x1d800
	s_nop 0
	global_load_lds_dwordx4 v[200:201], off offset:2048
	v_lshl_add_u64 v[134:135], v[134:135], 0, s[40:41]
	v_lshl_add_u64 v[200:201], v[200:201], 0, s[40:41]
	s_waitcnt lgkmcnt(8)
	v_mfma_f32_32x32x16_bf16 v[50:65], v[136:139], v[184:187], v[50:65]
	ds_read_b64_tr_b16 v[246:247], v170 offset:36864
	ds_read_b64_tr_b16 v[248:249], v173 offset:36864
	v_exp_f32_e32 v66, v66
	v_exp_f32_e32 v67, v67
	v_exp_f32_e32 v68, v68
	v_mfma_f32_32x32x16_bf16 v[34:49], v[140:143], v[184:187], v[34:49]
	ds_read_b64_tr_b16 v[250:251], v169 offset:36864
	ds_read_b64_tr_b16 v[252:253], v171 offset:36864
	v_exp_f32_e32 v69, v69
	v_exp_f32_e32 v70, v70
	v_exp_f32_e32 v71, v71
	s_waitcnt lgkmcnt(8)
	v_mfma_f32_32x32x16_bf16 v[18:33], v[204:207], v[184:187], v[18:33]
	ds_read_b64_tr_b16 v[136:137], v168 offset:40960
	ds_read_b64_tr_b16 v[138:139], v175 offset:40960
	v_exp_f32_e32 v72, v72
	v_exp_f32_e32 v73, v73
	v_cvt_pk_bf16_f32 v192, v66, v67
	v_mfma_f32_32x32x16_bf16 v[2:17], v[208:211], v[184:187], v[2:17]
	ds_read_b64_tr_b16 v[140:141], v172 offset:40960
	ds_read_b64_tr_b16 v[142:143], v174 offset:40960
	v_cvt_pk_bf16_f32 v193, v68, v69
	v_cvt_pk_bf16_f32 v194, v70, v71
	v_cvt_pk_bf16_f32 v195, v72, v73
	s_waitcnt lgkmcnt(8)
	v_mfma_f32_32x32x16_bf16 v[50:65], v[238:241], v[188:191], v[50:65]
	ds_read_b64_tr_b16 v[204:205], v170 offset:40960
	ds_read_b64_tr_b16 v[206:207], v173 offset:40960
	v_exp_f32_e32 v74, v74
	v_exp_f32_e32 v75, v75
	v_exp_f32_e32 v76, v76
	v_mfma_f32_32x32x16_bf16 v[34:49], v[242:245], v[188:191], v[34:49]
	ds_read_b64_tr_b16 v[208:209], v169 offset:40960
	ds_read_b64_tr_b16 v[210:211], v171 offset:40960
	v_exp_f32_e32 v77, v77
	v_exp_f32_e32 v78, v78
	v_exp_f32_e32 v79, v79
	s_waitcnt lgkmcnt(8)
	v_mfma_f32_32x32x16_bf16 v[18:33], v[246:249], v[188:191], v[18:33]
	ds_read_b64_tr_b16 v[238:239], v168 offset:45056
	ds_read_b64_tr_b16 v[240:241], v175 offset:45056
	v_exp_f32_e32 v80, v80
	v_exp_f32_e32 v81, v81
	v_cvt_pk_bf16_f32 v196, v74, v75
	v_mfma_f32_32x32x16_bf16 v[2:17], v[250:253], v[188:191], v[2:17]
	ds_read_b64_tr_b16 v[242:243], v172 offset:45056
	ds_read_b64_tr_b16 v[244:245], v174 offset:45056
	v_cvt_pk_bf16_f32 v197, v76, v77
	v_cvt_pk_bf16_f32 v198, v78, v79
	v_cvt_pk_bf16_f32 v199, v80, v81
	s_waitcnt lgkmcnt(8)
	v_mfma_f32_32x32x16_bf16 v[50:65], v[136:139], v[192:195], v[50:65]
	ds_read_b64_tr_b16 v[246:247], v170 offset:45056
	ds_read_b64_tr_b16 v[248:249], v173 offset:45056
	v_mfma_f32_32x32x16_bf16 v[34:49], v[140:143], v[192:195], v[34:49]
	ds_read_b64_tr_b16 v[250:251], v169 offset:45056
	ds_read_b64_tr_b16 v[252:253], v171 offset:45056
	s_waitcnt lgkmcnt(8)
	v_mfma_f32_32x32x16_bf16 v[18:33], v[204:207], v[192:195], v[18:33]
	v_mfma_f32_32x32x16_bf16 v[2:17], v[208:211], v[192:195], v[2:17]
	s_waitcnt lgkmcnt(4)
	v_mfma_f32_32x32x16_bf16 v[50:65], v[238:241], v[196:199], v[50:65]
	v_mfma_f32_32x32x16_bf16 v[34:49], v[242:245], v[196:199], v[34:49]
	s_waitcnt lgkmcnt(0)
	v_mfma_f32_32x32x16_bf16 v[18:33], v[246:249], v[196:199], v[18:33]
	v_mfma_f32_32x32x16_bf16 v[2:17], v[250:253], v[196:199], v[2:17]
	ds_read_b128 v[136:139], v178 offset:16384
	ds_read_b128 v[140:143], v178 offset:24576
	ds_read_b128 v[204:207], v181 offset:16384
	ds_read_b128 v[208:211], v181 offset:24576
	ds_read_b128 v[238:241], v180 offset:16384
	ds_read_b128 v[242:245], v180 offset:24576
	ds_read_b128 v[246:249], v179 offset:16384
	ds_read_b128 v[250:253], v179 offset:24576
	s_waitcnt vmcnt(6)
	s_add_i32 s50, s50, 64
	s_barrier
; #define LAS __attribute__((address_space(3)))
; __device__ __forceinline__ float max3f(float a, float b, float c) { float r; asm("v_max3_f32 %0, %1, %2, %3" : "=v"(r) : "v"(a), "v"(b), "v"(c)); return r; }
; __device__ __forceinline__ int crow(int r, int hi) { return (r & 3) + 8 * (r >> 2) + 4 * hi; }
; __device__ __forceinline__ void attn_block(LAS unsigned char* lds, const bf16_t* P, bf16_t* mix, int b, int h, int qb, float lam, float outscale, const float* subln) {
;     ...
;             f32x16 s0, s1;
; #pragma unroll
;             for (int j = 0; j < 16; ++j) { s0[j] = 0.f; s1[j] = 0.f; }
;             bf16x8 ka[4][2];
; #pragma unroll
;             for (int ks = 0; ks < 4; ++ks) { ka[ks][0] = *(const LAS bf16x8*)(Kb + kbase[ks]); ka[ks][1] = *(const LAS bf16x8*)(Kb + kbase[ks] + 8192); }
;             __builtin_amdgcn_sched_barrier(0);
; #pragma unroll
;             for (int ks = 0; ks < 4; ++ks) {
;                 s0 = __builtin_amdgcn_mfma_f32_32x32x16_bf16(ka[ks][0], qf[ks], s0, 0, 0, 0);
;                 s1 = __builtin_amdgcn_mfma_f32_32x32x16_bf16(ka[ks][1], qf[ks], s1, 0, 0, 0);
;             }
;             if (kb + 63 > qw0) {
; #pragma unroll
;                 for (int j = 0; j < 16; ++j) { const int key = kb + crow(j, hi); if (key > qrow) s0[j] = -INFINITY; if (key + 32 > qrow) s1[j] = -INFINITY; }
;             }
;             float mxa = max3f(s0[0], s1[0], s0[1]), mxb = max3f(s1[1], s0[2], s1[2]), mxc = max3f(s0[3], s1[3], s0[4]), mxd = max3f(s1[4], s0[5], s1[5]);
;             mxa = max3f(mxa, s0[6], s1[6]); mxb = max3f(mxb, s0[7], s1[7]); mxc = max3f(mxc, s0[8], s1[8]); mxd = max3f(mxd, s0[9], s1[9]);
;             mxa = max3f(mxa, s0[10], s1[10]); mxb = max3f(mxb, s0[11], s1[11]); mxc = max3f(mxc, s0[12], s1[12]); mxd = max3f(mxd, s0[13], s1[13]);
;             mxa = max3f(mxa, s0[14], s1[14]); mxb = max3f(mxb, s0[15], s1[15]);
;             float mx = max3f(mxa, mxb, max3f(mxc, mxd, mxd));
;             { auto rr = __builtin_amdgcn_permlane32_swap(__builtin_bit_cast(unsigned, mx), __builtin_bit_cast(unsigned, mx), false, false);
;               mx = fmaxf(__builtin_bit_cast(float, rr[0]), __builtin_bit_cast(float, rr[1])); }
;             if (__any(mx > mrun + 8.0f)) {
	s_add_i32 m0, s62, 0x0
	s_nop 0
	global_load_lds_dwordx4 v[134:135], off
	s_add_i32 m0, s62, 0x2000
	s_nop 0
	global_load_lds_dwordx4 v[200:201], off
	s_waitcnt lgkmcnt(7)
	v_mfma_f32_32x32x16_bf16 v[82:97], v[136:139], v[110:113], v[222:237]
	v_add_f32_e32 v122, v66, v67
	v_add_f32_e32 v123, v68, v69
	v_add_f32_e32 v122, v122, v70
	v_add_f32_e32 v123, v123, v71
	s_waitcnt lgkmcnt(5)
	v_mfma_f32_32x32x16_bf16 v[82:97], v[204:207], v[106:109], v[82:97]
	v_add_f32_e32 v122, v122, v72
	v_add_f32_e32 v123, v123, v73
	v_add_f32_e32 v122, v122, v123
	v_add_f32_e32 v167, v167, v122
	s_waitcnt lgkmcnt(3)
	v_mfma_f32_32x32x16_bf16 v[82:97], v[238:241], v[102:105], v[82:97]
	v_add_f32_e32 v122, v74, v75
	v_add_f32_e32 v123, v76, v77
	v_add_f32_e32 v122, v122, v78
	v_add_f32_e32 v123, v123, v79
	s_waitcnt lgkmcnt(1)
	v_mfma_f32_32x32x16_bf16 v[82:97], v[246:249], v[98:101], v[82:97]
	v_add_f32_e32 v122, v122, v80
	v_add_f32_e32 v123, v123, v81
	v_add_f32_e32 v122, v122, v123
	v_add_f32_e32 v167, v167, v122
	s_waitcnt lgkmcnt(0)
	v_mfma_f32_32x32x16_bf16 v[66:81], v[140:143], v[110:113], v[222:237]
	v_mfma_f32_32x32x16_bf16 v[66:81], v[208:211], v[106:109], v[66:81]
	v_mfma_f32_32x32x16_bf16 v[66:81], v[242:245], v[102:105], v[66:81]
	v_mfma_f32_32x32x16_bf16 v[66:81], v[250:253], v[98:101], v[66:81]
	ds_read_b64_tr_b16 v[136:137], v168 offset:49152
	ds_read_b64_tr_b16 v[138:139], v175 offset:49152
	ds_read_b64_tr_b16 v[140:141], v172 offset:49152
	ds_read_b64_tr_b16 v[142:143], v174 offset:49152
	ds_read_b64_tr_b16 v[204:205], v170 offset:49152
	ds_read_b64_tr_b16 v[206:207], v173 offset:49152
	ds_read_b64_tr_b16 v[208:209], v169 offset:49152
	ds_read_b64_tr_b16 v[210:211], v171 offset:49152
	ds_read_b64_tr_b16 v[238:239], v168 offset:53248
	ds_read_b64_tr_b16 v[240:241], v175 offset:53248
	ds_read_b64_tr_b16 v[242:243], v172 offset:53248
	ds_read_b64_tr_b16 v[244:245], v174 offset:53248
	s_nop 1
	v_max3_f32 v122, v82, v66, v83
	v_max3_f32 v123, v67, v84, v68
	v_max3_f32 v124, v85, v69, v86
	v_max3_f32 v125, v70, v87, v71
	v_max3_f32 v122, v122, v88, v72
	v_max3_f32 v123, v123, v89, v73
	v_max3_f32 v124, v124, v90, v74
	v_max3_f32 v125, v125, v91, v75
	v_max3_f32 v122, v122, v92, v76
	v_max3_f32 v123, v123, v93, v77
	v_max3_f32 v124, v124, v94, v78
	v_max3_f32 v125, v125, v95, v79
	v_max3_f32 v122, v122, v96, v80
	v_max3_f32 v123, v123, v97, v81
	v_max3_f32 v122, v122, v123, v124
	v_max_f32_e32 v122, v122, v125
	v_mov_b32_e32 v203, v122
	s_nop 1
	v_permlane32_swap_b32_e32 v122, v203
	s_nop 1
	v_max_f32_e32 v122, v122, v203
	s_mov_b32 s39, 0
	v_cmp_lt_f32_e32 vcc, 0x41000000, v122
	s_cmp_eq_u32 s50, 0
	s_cbranch_scc1 .Lat2_u1_first
	s_cbranch_vccz .Lat2_u1_norescale
	s_branch .Lat2_u1_rescale

; __device__ __forceinline__ unsigned pk2(float lo, float hi) { f32x2 v = {lo, hi}; bf16x2_t b = __builtin_convertvector(v, bf16x2_t); return __builtin_bit_cast(unsigned, b); }
; __device__ __forceinline__ s16x4 vtr(LAS const unsigned char* p) { return __builtin_bit_cast(s16x4, __builtin_amdgcn_ds_read_tr16_b64_v4i16((LAS v4i16_t*)p)); }
; __device__ __forceinline__ bf16x8 cat8(s16x4 a, s16x4 b) { return (bf16x8){a[0], a[1], a[2], a[3], b[0], b[1], b[2], b[3]}; }
; __device__ __forceinline__ void attn_block(LAS unsigned char* lds, const bf16_t* P, bf16_t* mix, int b, int h, int qb, float lam, float outscale, const float* subln) {
;     ...
;             for (int j = 0; j < 16; ++j) { s0[j] = __builtin_amdgcn_exp2f(s0[j] - mrun); s1[j] = __builtin_amdgcn_exp2f(s1[j] - mrun); }
;             float ps0 = 0.f, ps1 = 0.f, ps2 = 0.f, ps3 = 0.f;
; #pragma unroll
;             for (int j = 0; j < 16; j += 2) { ps0 += s0[j]; ps1 += s1[j]; ps2 += s0[j + 1]; ps3 += s1[j + 1]; }
;             lrun += (ps0 + ps1) + (ps2 + ps3);
;             bf16x8 pb[4];
; #pragma unroll
;             for (int s2 = 0; s2 < 2; ++s2) {
;                 u32x4 w0, w1;
;                 w0.x = pk2(s0[8 * s2 + 0], s0[8 * s2 + 1]); w0.y = pk2(s0[8 * s2 + 2], s0[8 * s2 + 3]); w0.z = pk2(s0[8 * s2 + 4], s0[8 * s2 + 5]); w0.w = pk2(s0[8 * s2 + 6], s0[8 * s2 + 7]);
;                 w1.x = pk2(s1[8 * s2 + 0], s1[8 * s2 + 1]); w1.y = pk2(s1[8 * s2 + 2], s1[8 * s2 + 3]); w1.z = pk2(s1[8 * s2 + 4], s1[8 * s2 + 5]); w1.w = pk2(s1[8 * s2 + 6], s1[8 * s2 + 7]);
;                 pb[s2] = __builtin_bit_cast(bf16x8, w0); pb[2 + s2] = __builtin_bit_cast(bf16x8, w1);
;             }
; #pragma unroll
;             for (int s = 0; s < 4; ++s) {
; #pragma unroll
;                 for (int c = 0; c < 4; ++c) {
;                     const s16x4 v0 = vtr(Vb + vbase[c][0] + 4096 * s);
;                     const s16x4 v1 = vtr(Vb + vbase[c][1] + 4096 * s);
;                     o[c] = __builtin_amdgcn_mfma_f32_32x32x16_bf16(cat8(v0, v1), pb[s], o[c], 0, 0, 0);
;                 }
;             }
.Lat2_u1_norescale:
	v_exp_f32_e32 v82, v82
	v_exp_f32_e32 v83, v83
	v_exp_f32_e32 v84, v84
	v_exp_f32_e32 v85, v85
	v_exp_f32_e32 v86, v86
	v_exp_f32_e32 v87, v87
	v_exp_f32_e32 v88, v88
	v_exp_f32_e32 v89, v89
	v_exp_f32_e32 v90, v90
	v_exp_f32_e32 v91, v91
	v_exp_f32_e32 v92, v92
	v_exp_f32_e32 v93, v93
	v_exp_f32_e32 v94, v94
	v_exp_f32_e32 v95, v95
	v_exp_f32_e32 v96, v96
	v_exp_f32_e32 v97, v97
	v_cvt_pk_bf16_f32 v184, v82, v83
	v_cvt_pk_bf16_f32 v185, v84, v85
	v_cvt_pk_bf16_f32 v186, v86, v87
	v_cvt_pk_bf16_f32 v187, v88, v89
	v_cvt_pk_bf16_f32 v188, v90, v91
	v_cvt_pk_bf16_f32 v189, v92, v93
	v_cvt_pk_bf16_f32 v190, v94, v95
	v_cvt_pk_bf16_f32 v191, v96, v97
	v_add_f32_e32 v122, v82, v83
	v_add_f32_e32 v123, v84, v85
	v_add_f32_e32 v122, v122, v86
	v_add_f32_e32 v123, v123, v87
	v_add_f32_e32 v122, v122, v88
	v_add_f32_e32 v123, v123, v89
	v_add_f32_e32 v122, v122, v123
	v_add_f32_e32 v167, v167, v122
	v_add_f32_e32 v124, v90, v91
	v_add_f32_e32 v125, v92, v93
	v_add_f32_e32 v124, v124, v94
	v_add_f32_e32 v125, v125, v95
	v_add_f32_e32 v124, v124, v96
	v_add_f32_e32 v125, v125, v97
	v_add_f32_e32 v124, v124, v125
	v_add_f32_e32 v167, v167, v124
	s_add_i32 m0, s62, 0x7800
	s_nop 0
	global_load_lds_dwordx4 v[134:135], off offset:2048
	s_add_i32 m0, s62, 0x9800
	s_nop 0
	global_load_lds_dwordx4 v[200:201], off offset:2048
	v_lshl_add_u64 v[134:135], v[134:135], 0, s[40:41]
	v_lshl_add_u64 v[200:201], v[200:201], 0, s[40:41]
	s_waitcnt lgkmcnt(8)
	v_mfma_f32_32x32x16_bf16 v[50:65], v[136:139], v[184:187], v[50:65]
	ds_read_b64_tr_b16 v[246:247], v170 offset:53248
	ds_read_b64_tr_b16 v[248:249], v173 offset:53248
	v_exp_f32_e32 v66, v66
	v_exp_f32_e32 v67, v67
	v_exp_f32_e32 v68, v68
	v_mfma_f32_32x32x16_bf16 v[34:49], v[140:143], v[184:187], v[34:49]
	ds_read_b64_tr_b16 v[250:251], v169 offset:53248
	ds_read_b64_tr_b16 v[252:253], v171 offset:53248
	v_exp_f32_e32 v69, v69
	v_exp_f32_e32 v70, v70
	v_exp_f32_e32 v71, v71
	s_waitcnt lgkmcnt(8)
	v_mfma_f32_32x32x16_bf16 v[18:33], v[204:207], v[184:187], v[18:33]
	ds_read_b64_tr_b16 v[136:137], v168 offset:57344
	ds_read_b64_tr_b16 v[138:139], v175 offset:57344
	v_exp_f32_e32 v72, v72
	v_exp_f32_e32 v73, v73
	v_cvt_pk_bf16_f32 v192, v66, v67
	v_mfma_f32_32x32x16_bf16 v[2:17], v[208:211], v[184:187], v[2:17]
	ds_read_b64_tr_b16 v[140:141], v172 offset:57344
	ds_read_b64_tr_b16 v[142:143], v174 offset:57344
	v_cvt_pk_bf16_f32 v193, v68, v69
	v_cvt_pk_bf16_f32 v194, v70, v71
	v_cvt_pk_bf16_f32 v195, v72, v73
	s_waitcnt lgkmcnt(8)
	v_mfma_f32_32x32x16_bf16 v[50:65], v[238:241], v[188:191], v[50:65]
	ds_read_b64_tr_b16 v[204:205], v170 offset:57344
	ds_read_b64_tr_b16 v[206:207], v173 offset:57344
	v_exp_f32_e32 v74, v74
	v_exp_f32_e32 v75, v75
	v_exp_f32_e32 v76, v76
	v_mfma_f32_32x32x16_bf16 v[34:49], v[242:245], v[188:191], v[34:49]
	ds_read_b64_tr_b16 v[208:209], v169 offset:57344
	ds_read_b64_tr_b16 v[210:211], v171 offset:57344
	v_exp_f32_e32 v77, v77
	v_exp_f32_e32 v78, v78
	v_exp_f32_e32 v79, v79
	s_waitcnt lgkmcnt(8)
	v_mfma_f32_32x32x16_bf16 v[18:33], v[246:249], v[188:191], v[18:33]
	ds_read_b64_tr_b16 v[238:239], v168 offset:61440
	ds_read_b64_tr_b16 v[240:241], v175 offset:61440
	v_exp_f32_e32 v80, v80
	v_exp_f32_e32 v81, v81
	v_cvt_pk_bf16_f32 v196, v74, v75
	v_mfma_f32_32x32x16_bf16 v[2:17], v[250:253], v[188:191], v[2:17]
	ds_read_b64_tr_b16 v[242:243], v172 offset:61440
	ds_read_b64_tr_b16 v[244:245], v174 offset:61440
	v_cvt_pk_bf16_f32 v197, v76, v77
	v_cvt_pk_bf16_f32 v198, v78, v79
	v_cvt_pk_bf16_f32 v199, v80, v81
	s_waitcnt lgkmcnt(8)
	v_mfma_f32_32x32x16_bf16 v[50:65], v[136:139], v[192:195], v[50:65]
	ds_read_b64_tr_b16 v[246:247], v170 offset:61440
	ds_read_b64_tr_b16 v[248:249], v173 offset:61440
	v_mfma_f32_32x32x16_bf16 v[34:49], v[140:143], v[192:195], v[34:49]
	ds_read_b64_tr_b16 v[250:251], v169 offset:61440
	ds_read_b64_tr_b16 v[252:253], v171 offset:61440
	s_waitcnt lgkmcnt(8)
	v_mfma_f32_32x32x16_bf16 v[18:33], v[204:207], v[192:195], v[18:33]
	v_mfma_f32_32x32x16_bf16 v[2:17], v[208:211], v[192:195], v[2:17]
	s_waitcnt lgkmcnt(4)
	v_mfma_f32_32x32x16_bf16 v[50:65], v[238:241], v[196:199], v[50:65]
	v_mfma_f32_32x32x16_bf16 v[34:49], v[242:245], v[196:199], v[34:49]
	s_waitcnt lgkmcnt(0)
	v_mfma_f32_32x32x16_bf16 v[18:33], v[246:249], v[196:199], v[18:33]
	v_mfma_f32_32x32x16_bf16 v[2:17], v[250:253], v[196:199], v[2:17]
	ds_read_b128 v[136:139], v126 offset:0
	ds_read_b128 v[140:143], v126 offset:8192
	ds_read_b128 v[204:207], v127 offset:0
	ds_read_b128 v[208:211], v127 offset:8192
	ds_read_b128 v[238:241], v128 offset:0
	ds_read_b128 v[242:245], v128 offset:8192
	ds_read_b128 v[246:249], v129 offset:0
	ds_read_b128 v[250:253], v129 offset:8192
	s_waitcnt vmcnt(6)
	s_add_i32 s50, s50, 64
	s_barrier
; #define LAS __attribute__((address_space(3)))
; __device__ __forceinline__ float max3f(float a, float b, float c) { float r; asm("v_max3_f32 %0, %1, %2, %3" : "=v"(r) : "v"(a), "v"(b), "v"(c)); return r; }
; __device__ __forceinline__ int crow(int r, int hi) { return (r & 3) + 8 * (r >> 2) + 4 * hi; }
; __device__ __forceinline__ void attn_block(LAS unsigned char* lds, const bf16_t* P, bf16_t* mix, int b, int h, int qb, float lam, float outscale, const float* subln) {
;     ...
;             f32x16 s0, s1;
; #pragma unroll
;             for (int j = 0; j < 16; ++j) { s0[j] = 0.f; s1[j] = 0.f; }
;             bf16x8 ka[4][2];
; #pragma unroll
;             for (int ks = 0; ks < 4; ++ks) { ka[ks][0] = *(const LAS bf16x8*)(Kb + kbase[ks]); ka[ks][1] = *(const LAS bf16x8*)(Kb + kbase[ks] + 8192); }
;             __builtin_amdgcn_sched_barrier(0);
; #pragma unroll
;             for (int ks = 0; ks < 4; ++ks) {
;                 s0 = __builtin_amdgcn_mfma_f32_32x32x16_bf16(ka[ks][0], qf[ks], s0, 0, 0, 0);
;                 s1 = __builtin_amdgcn_mfma_f32_32x32x16_bf16(ka[ks][1], qf[ks], s1, 0, 0, 0);
;             }
;             if (kb + 63 > qw0) {
; #pragma unroll
;                 for (int j = 0; j < 16; ++j) { const int key = kb + crow(j, hi); if (key > qrow) s0[j] = -INFINITY; if (key + 32 > qrow) s1[j] = -INFINITY; }
;             }
;             float mxa = max3f(s0[0], s1[0], s0[1]), mxb = max3f(s1[1], s0[2], s1[2]), mxc = max3f(s0[3], s1[3], s0[4]), mxd = max3f(s1[4], s0[5], s1[5]);
;             mxa = max3f(mxa, s0[6], s1[6]); mxb = max3f(mxb, s0[7], s1[7]); mxc = max3f(mxc, s0[8], s1[8]); mxd = max3f(mxd, s0[9], s1[9]);
;             mxa = max3f(mxa, s0[10], s1[10]); mxb = max3f(mxb, s0[11], s1[11]); mxc = max3f(mxc, s0[12], s1[12]); mxd = max3f(mxd, s0[13], s1[13]);
;             mxa = max3f(mxa, s0[14], s1[14]); mxb = max3f(mxb, s0[15], s1[15]);
;             float mx = max3f(mxa, mxb, max3f(mxc, mxd, mxd));
;             { auto rr = __builtin_amdgcn_permlane32_swap(__builtin_bit_cast(unsigned, mx), __builtin_bit_cast(unsigned, mx), false, false);
;               mx = fmaxf(__builtin_bit_cast(float, rr[0]), __builtin_bit_cast(float, rr[1])); }
;             if (__any(mx > mrun + 8.0f)) {
	s_add_i32 m0, s62, 0x4000
	s_nop 0
	global_load_lds_dwordx4 v[134:135], off
	s_add_i32 m0, s62, 0x6000
	s_nop 0
	global_load_lds_dwordx4 v[200:201], off
	s_waitcnt lgkmcnt(7)
	v_mfma_f32_32x32x16_bf16 v[82:97], v[136:139], v[110:113], v[222:237]
	v_add_f32_e32 v122, v66, v67
	v_add_f32_e32 v123, v68, v69
	v_add_f32_e32 v122, v122, v70
	v_add_f32_e32 v123, v123, v71
	s_waitcnt lgkmcnt(5)
	v_mfma_f32_32x32x16_bf16 v[82:97], v[204:207], v[106:109], v[82:97]
	v_add_f32_e32 v122, v122, v72
	v_add_f32_e32 v123, v123, v73
	v_add_f32_e32 v122, v122, v123
	v_add_f32_e32 v167, v167, v122
	s_waitcnt lgkmcnt(3)
	v_mfma_f32_32x32x16_bf16 v[82:97], v[238:241], v[102:105], v[82:97]
	v_add_f32_e32 v122, v74, v75
	v_add_f32_e32 v123, v76, v77
	v_add_f32_e32 v122, v122, v78
	v_add_f32_e32 v123, v123, v79
	s_waitcnt lgkmcnt(1)
	v_mfma_f32_32x32x16_bf16 v[82:97], v[246:249], v[98:101], v[82:97]
	v_add_f32_e32 v122, v122, v80
	v_add_f32_e32 v123, v123, v81
	v_add_f32_e32 v122, v122, v123
	v_add_f32_e32 v167, v167, v122
	s_waitcnt lgkmcnt(0)
	v_mfma_f32_32x32x16_bf16 v[66:81], v[140:143], v[110:113], v[222:237]
	v_mfma_f32_32x32x16_bf16 v[66:81], v[208:211], v[106:109], v[66:81]
	v_mfma_f32_32x32x16_bf16 v[66:81], v[242:245], v[102:105], v[66:81]
	v_mfma_f32_32x32x16_bf16 v[66:81], v[250:253], v[98:101], v[66:81]
	ds_read_b64_tr_b16 v[136:137], v114 offset:32768
	ds_read_b64_tr_b16 v[138:139], v115 offset:32768
	ds_read_b64_tr_b16 v[140:141], v116 offset:32768
	ds_read_b64_tr_b16 v[142:143], v117 offset:32768
	ds_read_b64_tr_b16 v[204:205], v118 offset:32768
	ds_read_b64_tr_b16 v[206:207], v119 offset:32768
	ds_read_b64_tr_b16 v[208:209], v120 offset:32768
	ds_read_b64_tr_b16 v[210:211], v121 offset:32768
	ds_read_b64_tr_b16 v[238:239], v114 offset:36864
	ds_read_b64_tr_b16 v[240:241], v115 offset:36864
	ds_read_b64_tr_b16 v[242:243], v116 offset:36864
	ds_read_b64_tr_b16 v[244:245], v117 offset:36864
	s_nop 1
	v_max3_f32 v122, v82, v66, v83
	v_max3_f32 v123, v67, v84, v68
	v_max3_f32 v124, v85, v69, v86
	v_max3_f32 v125, v70, v87, v71
	v_max3_f32 v122, v122, v88, v72
	v_max3_f32 v123, v123, v89, v73
	v_max3_f32 v124, v124, v90, v74
	v_max3_f32 v125, v125, v91, v75
	v_max3_f32 v122, v122, v92, v76
	v_max3_f32 v123, v123, v93, v77
	v_max3_f32 v124, v124, v94, v78
	v_max3_f32 v125, v125, v95, v79
	v_max3_f32 v122, v122, v96, v80
	v_max3_f32 v123, v123, v97, v81
	v_max3_f32 v122, v122, v123, v124
	v_max_f32_e32 v122, v122, v125
	v_mov_b32_e32 v203, v122
	s_nop 1
	v_permlane32_swap_b32_e32 v122, v203
	s_nop 1
	v_max_f32_e32 v122, v122, v203
	s_mov_b32 s39, 0
	v_cmp_lt_f32_e32 vcc, 0x41000000, v122
	s_cmp_eq_u32 s50, 0
	s_cbranch_scc1 .Lat2_u2_first
	s_cbranch_vccz .Lat2_u2_norescale
	s_branch .Lat2_u2_rescale

; __device__ __forceinline__ unsigned pk2(float lo, float hi) { f32x2 v = {lo, hi}; bf16x2_t b = __builtin_convertvector(v, bf16x2_t); return __builtin_bit_cast(unsigned, b); }
; __device__ __forceinline__ s16x4 vtr(LAS const unsigned char* p) { return __builtin_bit_cast(s16x4, __builtin_amdgcn_ds_read_tr16_b64_v4i16((LAS v4i16_t*)p)); }
; __device__ __forceinline__ bf16x8 cat8(s16x4 a, s16x4 b) { return (bf16x8){a[0], a[1], a[2], a[3], b[0], b[1], b[2], b[3]}; }
; __device__ __forceinline__ void attn_block(LAS unsigned char* lds, const bf16_t* P, bf16_t* mix, int b, int h, int qb, float lam, float outscale, const float* subln) {
;     ...
;             for (int j = 0; j < 16; ++j) { s0[j] = __builtin_amdgcn_exp2f(s0[j] - mrun); s1[j] = __builtin_amdgcn_exp2f(s1[j] - mrun); }
;             float ps0 = 0.f, ps1 = 0.f, ps2 = 0.f, ps3 = 0.f;
; #pragma unroll
;             for (int j = 0; j < 16; j += 2) { ps0 += s0[j]; ps1 += s1[j]; ps2 += s0[j + 1]; ps3 += s1[j + 1]; }
;             lrun += (ps0 + ps1) + (ps2 + ps3);
;             bf16x8 pb[4];
; #pragma unroll
;             for (int s2 = 0; s2 < 2; ++s2) {
;                 u32x4 w0, w1;
;                 w0.x = pk2(s0[8 * s2 + 0], s0[8 * s2 + 1]); w0.y = pk2(s0[8 * s2 + 2], s0[8 * s2 + 3]); w0.z = pk2(s0[8 * s2 + 4], s0[8 * s2 + 5]); w0.w = pk2(s0[8 * s2 + 6], s0[8 * s2 + 7]);
;                 w1.x = pk2(s1[8 * s2 + 0], s1[8 * s2 + 1]); w1.y = pk2(s1[8 * s2 + 2], s1[8 * s2 + 3]); w1.z = pk2(s1[8 * s2 + 4], s1[8 * s2 + 5]); w1.w = pk2(s1[8 * s2 + 6], s1[8 * s2 + 7]);
;                 pb[s2] = __builtin_bit_cast(bf16x8, w0); pb[2 + s2] = __builtin_bit_cast(bf16x8, w1);
;             }
; #pragma unroll
;             for (int s = 0; s < 4; ++s) {
; #pragma unroll
;                 for (int c = 0; c < 4; ++c) {
;                     const s16x4 v0 = vtr(Vb + vbase[c][0] + 4096 * s);
;                     const s16x4 v1 = vtr(Vb + vbase[c][1] + 4096 * s);
;                     o[c] = __builtin_amdgcn_mfma_f32_32x32x16_bf16(cat8(v0, v1), pb[s], o[c], 0, 0, 0);
;                 }
;             }
.Lat2_u2_norescale:
	v_exp_f32_e32 v82, v82
	v_exp_f32_e32 v83, v83
	v_exp_f32_e32 v84, v84
	v_exp_f32_e32 v85, v85
	v_exp_f32_e32 v86, v86
	v_exp_f32_e32 v87, v87
	v_exp_f32_e32 v88, v88
	v_exp_f32_e32 v89, v89
	v_exp_f32_e32 v90, v90
	v_exp_f32_e32 v91, v91
	v_exp_f32_e32 v92, v92
	v_exp_f32_e32 v93, v93
	v_exp_f32_e32 v94, v94
	v_exp_f32_e32 v95, v95
	v_exp_f32_e32 v96, v96
	v_exp_f32_e32 v97, v97
	v_cvt_pk_bf16_f32 v184, v82, v83
	v_cvt_pk_bf16_f32 v185, v84, v85
	v_cvt_pk_bf16_f32 v186, v86, v87
	v_cvt_pk_bf16_f32 v187, v88, v89
	v_cvt_pk_bf16_f32 v188, v90, v91
	v_cvt_pk_bf16_f32 v189, v92, v93
	v_cvt_pk_bf16_f32 v190, v94, v95
	v_cvt_pk_bf16_f32 v191, v96, v97
	v_add_f32_e32 v122, v82, v83
	v_add_f32_e32 v123, v84, v85
	v_add_f32_e32 v122, v122, v86
	v_add_f32_e32 v123, v123, v87
	v_add_f32_e32 v122, v122, v88
	v_add_f32_e32 v123, v123, v89
	v_add_f32_e32 v122, v122, v123
	v_add_f32_e32 v167, v167, v122
	v_add_f32_e32 v124, v90, v91
	v_add_f32_e32 v125, v92, v93
	v_add_f32_e32 v124, v124, v94
	v_add_f32_e32 v125, v125, v95
	v_add_f32_e32 v124, v124, v96
	v_add_f32_e32 v125, v125, v97
	v_add_f32_e32 v124, v124, v125
	v_add_f32_e32 v167, v167, v124
	s_add_i32 m0, s62, 0xb800
	s_nop 0
	global_load_lds_dwordx4 v[134:135], off offset:2048
	s_add_i32 m0, s62, 0xd800
	s_nop 0
	global_load_lds_dwordx4 v[200:201], off offset:2048
	v_lshl_add_u64 v[134:135], v[134:135], 0, s[40:41]
	v_lshl_add_u64 v[200:201], v[200:201], 0, s[40:41]
	s_waitcnt lgkmcnt(8)
	v_mfma_f32_32x32x16_bf16 v[50:65], v[136:139], v[184:187], v[50:65]
	ds_read_b64_tr_b16 v[246:247], v118 offset:36864
	ds_read_b64_tr_b16 v[248:249], v119 offset:36864
	v_exp_f32_e32 v66, v66
	v_exp_f32_e32 v67, v67
	v_exp_f32_e32 v68, v68
	v_mfma_f32_32x32x16_bf16 v[34:49], v[140:143], v[184:187], v[34:49]
	ds_read_b64_tr_b16 v[250:251], v120 offset:36864
	ds_read_b64_tr_b16 v[252:253], v121 offset:36864
	v_exp_f32_e32 v69, v69
	v_exp_f32_e32 v70, v70
	v_exp_f32_e32 v71, v71
	s_waitcnt lgkmcnt(8)
	v_mfma_f32_32x32x16_bf16 v[18:33], v[204:207], v[184:187], v[18:33]
	ds_read_b64_tr_b16 v[136:137], v114 offset:40960
	ds_read_b64_tr_b16 v[138:139], v115 offset:40960
	v_exp_f32_e32 v72, v72
	v_exp_f32_e32 v73, v73
	v_cvt_pk_bf16_f32 v192, v66, v67
	v_mfma_f32_32x32x16_bf16 v[2:17], v[208:211], v[184:187], v[2:17]
	ds_read_b64_tr_b16 v[140:141], v116 offset:40960
	ds_read_b64_tr_b16 v[142:143], v117 offset:40960
	v_cvt_pk_bf16_f32 v193, v68, v69
	v_cvt_pk_bf16_f32 v194, v70, v71
	v_cvt_pk_bf16_f32 v195, v72, v73
	s_waitcnt lgkmcnt(8)
	v_mfma_f32_32x32x16_bf16 v[50:65], v[238:241], v[188:191], v[50:65]
	ds_read_b64_tr_b16 v[204:205], v118 offset:40960
	ds_read_b64_tr_b16 v[206:207], v119 offset:40960
	v_exp_f32_e32 v74, v74
	v_exp_f32_e32 v75, v75
	v_exp_f32_e32 v76, v76
	v_mfma_f32_32x32x16_bf16 v[34:49], v[242:245], v[188:191], v[34:49]
	ds_read_b64_tr_b16 v[208:209], v120 offset:40960
	ds_read_b64_tr_b16 v[210:211], v121 offset:40960
	v_exp_f32_e32 v77, v77
	v_exp_f32_e32 v78, v78
	v_exp_f32_e32 v79, v79
	s_waitcnt lgkmcnt(8)
	v_mfma_f32_32x32x16_bf16 v[18:33], v[246:249], v[188:191], v[18:33]
	ds_read_b64_tr_b16 v[238:239], v114 offset:45056
	ds_read_b64_tr_b16 v[240:241], v115 offset:45056
	v_exp_f32_e32 v80, v80
	v_exp_f32_e32 v81, v81
	v_cvt_pk_bf16_f32 v196, v74, v75
	v_mfma_f32_32x32x16_bf16 v[2:17], v[250:253], v[188:191], v[2:17]
	ds_read_b64_tr_b16 v[242:243], v116 offset:45056
	ds_read_b64_tr_b16 v[244:245], v117 offset:45056
	v_cvt_pk_bf16_f32 v197, v76, v77
	v_cvt_pk_bf16_f32 v198, v78, v79
	v_cvt_pk_bf16_f32 v199, v80, v81
	s_waitcnt lgkmcnt(8)
	v_mfma_f32_32x32x16_bf16 v[50:65], v[136:139], v[192:195], v[50:65]
	ds_read_b64_tr_b16 v[246:247], v118 offset:45056
	ds_read_b64_tr_b16 v[248:249], v119 offset:45056
	v_mfma_f32_32x32x16_bf16 v[34:49], v[140:143], v[192:195], v[34:49]
	ds_read_b64_tr_b16 v[250:251], v120 offset:45056
	ds_read_b64_tr_b16 v[252:253], v121 offset:45056
	s_waitcnt lgkmcnt(8)
	v_mfma_f32_32x32x16_bf16 v[18:33], v[204:207], v[192:195], v[18:33]
	v_mfma_f32_32x32x16_bf16 v[2:17], v[208:211], v[192:195], v[2:17]
	s_waitcnt lgkmcnt(4)
	v_mfma_f32_32x32x16_bf16 v[50:65], v[238:241], v[196:199], v[50:65]
	v_mfma_f32_32x32x16_bf16 v[34:49], v[242:245], v[196:199], v[34:49]
	s_waitcnt lgkmcnt(0)
	v_mfma_f32_32x32x16_bf16 v[18:33], v[246:249], v[196:199], v[18:33]
	v_mfma_f32_32x32x16_bf16 v[2:17], v[250:253], v[196:199], v[2:17]
	ds_read_b128 v[136:139], v126 offset:16384
	ds_read_b128 v[140:143], v126 offset:24576
	ds_read_b128 v[204:207], v127 offset:16384
	ds_read_b128 v[208:211], v127 offset:24576
	ds_read_b128 v[238:241], v128 offset:16384
	ds_read_b128 v[242:245], v128 offset:24576
	ds_read_b128 v[246:249], v129 offset:16384
	ds_read_b128 v[250:253], v129 offset:24576
	s_waitcnt vmcnt(6)
	s_add_i32 s50, s50, 64
	s_barrier
; #define LAS __attribute__((address_space(3)))
; __device__ __forceinline__ float max3f(float a, float b, float c) { float r; asm("v_max3_f32 %0, %1, %2, %3" : "=v"(r) : "v"(a), "v"(b), "v"(c)); return r; }
; __device__ __forceinline__ int crow(int r, int hi) { return (r & 3) + 8 * (r >> 2) + 4 * hi; }
; __device__ __forceinline__ void attn_block(LAS unsigned char* lds, const bf16_t* P, bf16_t* mix, int b, int h, int qb, float lam, float outscale, const float* subln) {
;     ...
;             f32x16 s0, s1;
; #pragma unroll
;             for (int j = 0; j < 16; ++j) { s0[j] = 0.f; s1[j] = 0.f; }
;             bf16x8 ka[4][2];
; #pragma unroll
;             for (int ks = 0; ks < 4; ++ks) { ka[ks][0] = *(const LAS bf16x8*)(Kb + kbase[ks]); ka[ks][1] = *(const LAS bf16x8*)(Kb + kbase[ks] + 8192); }
;             __builtin_amdgcn_sched_barrier(0);
; #pragma unroll
;             for (int ks = 0; ks < 4; ++ks) {
;                 s0 = __builtin_amdgcn_mfma_f32_32x32x16_bf16(ka[ks][0], qf[ks], s0, 0, 0, 0);
;                 s1 = __builtin_amdgcn_mfma_f32_32x32x16_bf16(ka[ks][1], qf[ks], s1, 0, 0, 0);
;             }
;             if (kb + 63 > qw0) {
; #pragma unroll
;                 for (int j = 0; j < 16; ++j) { const int key = kb + crow(j, hi); if (key > qrow) s0[j] = -INFINITY; if (key + 32 > qrow) s1[j] = -INFINITY; }
;             }
;             float mxa = max3f(s0[0], s1[0], s0[1]), mxb = max3f(s1[1], s0[2], s1[2]), mxc = max3f(s0[3], s1[3], s0[4]), mxd = max3f(s1[4], s0[5], s1[5]);
;             mxa = max3f(mxa, s0[6], s1[6]); mxb = max3f(mxb, s0[7], s1[7]); mxc = max3f(mxc, s0[8], s1[8]); mxd = max3f(mxd, s0[9], s1[9]);
;             mxa = max3f(mxa, s0[10], s1[10]); mxb = max3f(mxb, s0[11], s1[11]); mxc = max3f(mxc, s0[12], s1[12]); mxd = max3f(mxd, s0[13], s1[13]);
;             mxa = max3f(mxa, s0[14], s1[14]); mxb = max3f(mxb, s0[15], s1[15]);
;             float mx = max3f(mxa, mxb, max3f(mxc, mxd, mxd));
;             { auto rr = __builtin_amdgcn_permlane32_swap(__builtin_bit_cast(unsigned, mx), __builtin_bit_cast(unsigned, mx), false, false);
;               mx = fmaxf(__builtin_bit_cast(float, rr[0]), __builtin_bit_cast(float, rr[1])); }
;             if (__any(mx > mrun + 8.0f)) {
	s_add_i32 m0, s62, 0x10000
	s_nop 0
	global_load_lds_dwordx4 v[134:135], off
	s_add_i32 m0, s62, 0x12000
	s_nop 0
	global_load_lds_dwordx4 v[200:201], off
	s_waitcnt lgkmcnt(7)
	v_mfma_f32_32x32x16_bf16 v[82:97], v[136:139], v[110:113], v[222:237]
	v_add_f32_e32 v122, v66, v67
	v_add_f32_e32 v123, v68, v69
	v_add_f32_e32 v122, v122, v70
	v_add_f32_e32 v123, v123, v71
	s_waitcnt lgkmcnt(5)
	v_mfma_f32_32x32x16_bf16 v[82:97], v[204:207], v[106:109], v[82:97]
	v_add_f32_e32 v122, v122, v72
	v_add_f32_e32 v123, v123, v73
	v_add_f32_e32 v122, v122, v123
	v_add_f32_e32 v167, v167, v122
	s_waitcnt lgkmcnt(3)
	v_mfma_f32_32x32x16_bf16 v[82:97], v[238:241], v[102:105], v[82:97]
	v_add_f32_e32 v122, v74, v75
	v_add_f32_e32 v123, v76, v77
	v_add_f32_e32 v122, v122, v78
	v_add_f32_e32 v123, v123, v79
	s_waitcnt lgkmcnt(1)
	v_mfma_f32_32x32x16_bf16 v[82:97], v[246:249], v[98:101], v[82:97]
	v_add_f32_e32 v122, v122, v80
	v_add_f32_e32 v123, v123, v81
	v_add_f32_e32 v122, v122, v123
	v_add_f32_e32 v167, v167, v122
	s_waitcnt lgkmcnt(0)
	v_mfma_f32_32x32x16_bf16 v[66:81], v[140:143], v[110:113], v[222:237]
	v_mfma_f32_32x32x16_bf16 v[66:81], v[208:211], v[106:109], v[66:81]
	v_mfma_f32_32x32x16_bf16 v[66:81], v[242:245], v[102:105], v[66:81]
	v_mfma_f32_32x32x16_bf16 v[66:81], v[250:253], v[98:101], v[66:81]
	ds_read_b64_tr_b16 v[136:137], v114 offset:49152
	ds_read_b64_tr_b16 v[138:139], v115 offset:49152
	ds_read_b64_tr_b16 v[140:141], v116 offset:49152
	ds_read_b64_tr_b16 v[142:143], v117 offset:49152
	ds_read_b64_tr_b16 v[204:205], v118 offset:49152
	ds_read_b64_tr_b16 v[206:207], v119 offset:49152
	ds_read_b64_tr_b16 v[208:209], v120 offset:49152
	ds_read_b64_tr_b16 v[210:211], v121 offset:49152
	ds_read_b64_tr_b16 v[238:239], v114 offset:53248
	ds_read_b64_tr_b16 v[240:241], v115 offset:53248
	ds_read_b64_tr_b16 v[242:243], v116 offset:53248
	ds_read_b64_tr_b16 v[244:245], v117 offset:53248
	s_nop 1
	v_max3_f32 v122, v82, v66, v83
	v_max3_f32 v123, v67, v84, v68
	v_max3_f32 v124, v85, v69, v86
	v_max3_f32 v125, v70, v87, v71
	v_max3_f32 v122, v122, v88, v72
	v_max3_f32 v123, v123, v89, v73
	v_max3_f32 v124, v124, v90, v74
	v_max3_f32 v125, v125, v91, v75
	v_max3_f32 v122, v122, v92, v76
	v_max3_f32 v123, v123, v93, v77
	v_max3_f32 v124, v124, v94, v78
	v_max3_f32 v125, v125, v95, v79
	v_max3_f32 v122, v122, v96, v80
	v_max3_f32 v123, v123, v97, v81
	v_max3_f32 v122, v122, v123, v124
	v_max_f32_e32 v122, v122, v125
	v_mov_b32_e32 v203, v122
	s_nop 1
	v_permlane32_swap_b32_e32 v122, v203
	s_nop 1
	v_max_f32_e32 v122, v122, v203
	s_mov_b32 s39, 0
	v_cmp_lt_f32_e32 vcc, 0x41000000, v122
	s_cmp_eq_u32 s50, 0
	s_cbranch_scc1 .Lat2_u3_first
	s_cbranch_vccz .Lat2_u3_norescale
	s_branch .Lat2_u3_rescale

; #define LAS __attribute__((address_space(3)))
; __device__ __forceinline__ unsigned pk2(float lo, float hi) { f32x2 v = {lo, hi}; bf16x2_t b = __builtin_convertvector(v, bf16x2_t); return __builtin_bit_cast(unsigned, b); }
; __device__ __forceinline__ s16x4 vtr(LAS const unsigned char* p) { return __builtin_bit_cast(s16x4, __builtin_amdgcn_ds_read_tr16_b64_v4i16((LAS v4i16_t*)p)); }
; __device__ __forceinline__ void attn_block(LAS unsigned char* lds, const bf16_t* P, bf16_t* mix, int b, int h, int qb, float lam, float outscale, const float* subln) {
;     ...
;             for (int j = 0; j < 16; ++j) { s0[j] = __builtin_amdgcn_exp2f(s0[j] - mrun); s1[j] = __builtin_amdgcn_exp2f(s1[j] - mrun); }
;             float ps0 = 0.f, ps1 = 0.f, ps2 = 0.f, ps3 = 0.f;
; #pragma unroll
;             for (int j = 0; j < 16; j += 2) { ps0 += s0[j]; ps1 += s1[j]; ps2 += s0[j + 1]; ps3 += s1[j + 1]; }
;             lrun += (ps0 + ps1) + (ps2 + ps3);
;             bf16x8 pb[4];
; #pragma unroll
;             for (int s2 = 0; s2 < 2; ++s2) {
;                 u32x4 w0, w1;
;                 w0.x = pk2(s0[8 * s2 + 0], s0[8 * s2 + 1]); w0.y = pk2(s0[8 * s2 + 2], s0[8 * s2 + 3]); w0.z = pk2(s0[8 * s2 + 4], s0[8 * s2 + 5]); w0.w = pk2(s0[8 * s2 + 6], s0[8 * s2 + 7]);
;                 w1.x = pk2(s1[8 * s2 + 0], s1[8 * s2 + 1]); w1.y = pk2(s1[8 * s2 + 2], s1[8 * s2 + 3]); w1.z = pk2(s1[8 * s2 + 4], s1[8 * s2 + 5]); w1.w = pk2(s1[8 * s2 + 6], s1[8 * s2 + 7]);
;                 pb[s2] = __builtin_bit_cast(bf16x8, w0); pb[2 + s2] = __builtin_bit_cast(bf16x8, w1);
;             }
; #pragma unroll
;             for (int s = 0; s < 4; ++s) {
; #pragma unroll
;                 for (int c = 0; c < 4; ++c) {
;                     const s16x4 v0 = vtr(Vb + vbase[c][0] + 4096 * s);
;                     const s16x4 v1 = vtr(Vb + vbase[c][1] + 4096 * s);
;                     o[c] = __builtin_amdgcn_mfma_f32_32x32x16_bf16(cat8(v0, v1), pb[s], o[c], 0, 0, 0);
;                 }
;             }
;         }
;         if (kt + 1 < ntiles) {
;             const int nb = (kt + 1) & 1;
;             *(LAS u32x4*)(lds + ATT_K0 + nb * 16384 + so0) = kr0; *(LAS u32x4*)(lds + ATT_K0 + nb * 16384 + so1) = kr1;
;             *(LAS u32x4*)(lds + ATT_V0 + nb * 16384 + so0) = vr0; *(LAS u32x4*)(lds + ATT_V0 + nb * 16384 + so1) = vr1;
;         }
;     }
.Lat2_u3_norescale:
	v_exp_f32_e32 v82, v82
	v_exp_f32_e32 v83, v83
	v_exp_f32_e32 v84, v84
	v_exp_f32_e32 v85, v85
	v_exp_f32_e32 v86, v86
	v_exp_f32_e32 v87, v87
	v_exp_f32_e32 v88, v88
	v_exp_f32_e32 v89, v89
	v_exp_f32_e32 v90, v90
	v_exp_f32_e32 v91, v91
	v_exp_f32_e32 v92, v92
	v_exp_f32_e32 v93, v93
	v_exp_f32_e32 v94, v94
	v_exp_f32_e32 v95, v95
	v_exp_f32_e32 v96, v96
	v_exp_f32_e32 v97, v97
	v_cvt_pk_bf16_f32 v184, v82, v83
	v_cvt_pk_bf16_f32 v185, v84, v85
	v_cvt_pk_bf16_f32 v186, v86, v87
	v_cvt_pk_bf16_f32 v187, v88, v89
	v_cvt_pk_bf16_f32 v188, v90, v91
	v_cvt_pk_bf16_f32 v189, v92, v93
	v_cvt_pk_bf16_f32 v190, v94, v95
	v_cvt_pk_bf16_f32 v191, v96, v97
	v_add_f32_e32 v122, v82, v83
	v_add_f32_e32 v123, v84, v85
	v_add_f32_e32 v122, v122, v86
	v_add_f32_e32 v123, v123, v87
	v_add_f32_e32 v122, v122, v88
	v_add_f32_e32 v123, v123, v89
	v_add_f32_e32 v122, v122, v123
	v_add_f32_e32 v167, v167, v122
	v_add_f32_e32 v124, v90, v91
	v_add_f32_e32 v125, v92, v93
	v_add_f32_e32 v124, v124, v94
	v_add_f32_e32 v125, v125, v95
	v_add_f32_e32 v124, v124, v96
	v_add_f32_e32 v125, v125, v97
	v_add_f32_e32 v124, v124, v125
	v_add_f32_e32 v167, v167, v124
	s_add_i32 m0, s62, 0x17800
	s_nop 0
	global_load_lds_dwordx4 v[134:135], off offset:2048
	s_add_i32 m0, s62, 0x19800
	s_nop 0
	global_load_lds_dwordx4 v[200:201], off offset:2048
	v_lshl_add_u64 v[134:135], v[134:135], 0, s[40:41]
	v_lshl_add_u64 v[200:201], v[200:201], 0, s[40:41]
	s_waitcnt lgkmcnt(8)
	v_mfma_f32_32x32x16_bf16 v[50:65], v[136:139], v[184:187], v[50:65]
	ds_read_b64_tr_b16 v[246:247], v118 offset:53248
	ds_read_b64_tr_b16 v[248:249], v119 offset:53248
	v_exp_f32_e32 v66, v66
	v_exp_f32_e32 v67, v67
	v_exp_f32_e32 v68, v68
	v_mfma_f32_32x32x16_bf16 v[34:49], v[140:143], v[184:187], v[34:49]
	ds_read_b64_tr_b16 v[250:251], v120 offset:53248
	ds_read_b64_tr_b16 v[252:253], v121 offset:53248
	v_exp_f32_e32 v69, v69
	v_exp_f32_e32 v70, v70
	v_exp_f32_e32 v71, v71
	s_waitcnt lgkmcnt(8)
	v_mfma_f32_32x32x16_bf16 v[18:33], v[204:207], v[184:187], v[18:33]
	ds_read_b64_tr_b16 v[136:137], v114 offset:57344
	ds_read_b64_tr_b16 v[138:139], v115 offset:57344
	v_exp_f32_e32 v72, v72
	v_exp_f32_e32 v73, v73
	v_cvt_pk_bf16_f32 v192, v66, v67
	v_mfma_f32_32x32x16_bf16 v[2:17], v[208:211], v[184:187], v[2:17]
	ds_read_b64_tr_b16 v[140:141], v116 offset:57344
	ds_read_b64_tr_b16 v[142:143], v117 offset:57344
	v_cvt_pk_bf16_f32 v193, v68, v69
	v_cvt_pk_bf16_f32 v194, v70, v71
	v_cvt_pk_bf16_f32 v195, v72, v73
	s_waitcnt lgkmcnt(8)
	v_mfma_f32_32x32x16_bf16 v[50:65], v[238:241], v[188:191], v[50:65]
	ds_read_b64_tr_b16 v[204:205], v118 offset:57344
	ds_read_b64_tr_b16 v[206:207], v119 offset:57344
	v_exp_f32_e32 v74, v74
	v_exp_f32_e32 v75, v75
	v_exp_f32_e32 v76, v76
	v_mfma_f32_32x32x16_bf16 v[34:49], v[242:245], v[188:191], v[34:49]
	ds_read_b64_tr_b16 v[208:209], v120 offset:57344
	ds_read_b64_tr_b16 v[210:211], v121 offset:57344
	v_exp_f32_e32 v77, v77
	v_exp_f32_e32 v78, v78
	v_exp_f32_e32 v79, v79
	s_waitcnt lgkmcnt(8)
	v_mfma_f32_32x32x16_bf16 v[18:33], v[246:249], v[188:191], v[18:33]
	ds_read_b64_tr_b16 v[238:239], v114 offset:61440
	ds_read_b64_tr_b16 v[240:241], v115 offset:61440
	v_exp_f32_e32 v80, v80
	v_exp_f32_e32 v81, v81
	v_cvt_pk_bf16_f32 v196, v74, v75
	v_mfma_f32_32x32x16_bf16 v[2:17], v[250:253], v[188:191], v[2:17]
	ds_read_b64_tr_b16 v[242:243], v116 offset:61440
	ds_read_b64_tr_b16 v[244:245], v117 offset:61440
	v_cvt_pk_bf16_f32 v197, v76, v77
	v_cvt_pk_bf16_f32 v198, v78, v79
	v_cvt_pk_bf16_f32 v199, v80, v81
	s_waitcnt lgkmcnt(8)
	v_mfma_f32_32x32x16_bf16 v[50:65], v[136:139], v[192:195], v[50:65]
	ds_read_b64_tr_b16 v[246:247], v118 offset:61440
	ds_read_b64_tr_b16 v[248:249], v119 offset:61440
	v_mfma_f32_32x32x16_bf16 v[34:49], v[140:143], v[192:195], v[34:49]
	ds_read_b64_tr_b16 v[250:251], v120 offset:61440
	ds_read_b64_tr_b16 v[252:253], v121 offset:61440
	s_waitcnt lgkmcnt(8)
	v_mfma_f32_32x32x16_bf16 v[18:33], v[204:207], v[192:195], v[18:33]
	v_mfma_f32_32x32x16_bf16 v[2:17], v[208:211], v[192:195], v[2:17]
	s_waitcnt lgkmcnt(4)
	v_mfma_f32_32x32x16_bf16 v[50:65], v[238:241], v[196:199], v[50:65]
	v_mfma_f32_32x32x16_bf16 v[34:49], v[242:245], v[196:199], v[34:49]
	s_waitcnt lgkmcnt(0)
	v_mfma_f32_32x32x16_bf16 v[18:33], v[246:249], v[196:199], v[18:33]
	v_mfma_f32_32x32x16_bf16 v[2:17], v[250:253], v[196:199], v[2:17]
	ds_read_b128 v[136:139], v178 offset:0
	ds_read_b128 v[140:143], v178 offset:8192
	ds_read_b128 v[204:207], v181 offset:0
	ds_read_b128 v[208:211], v181 offset:8192
	ds_read_b128 v[238:241], v180 offset:0
	ds_read_b128 v[242:245], v180 offset:8192
	ds_read_b128 v[246:249], v179 offset:0
	ds_read_b128 v[250:253], v179 offset:8192
	s_waitcnt vmcnt(6)
	s_add_i32 s50, s50, 64
	s_add_i32 s51, s50, 384
	s_cmp_le_u32 s51, s2
	s_barrier
	s_cbranch_scc1 .Lat2_U_top
	v_add_f32_e32 v122, v66, v67
	v_add_f32_e32 v123, v68, v69
	v_add_f32_e32 v122, v122, v70
	v_add_f32_e32 v123, v123, v71
	v_add_f32_e32 v122, v122, v72
	v_add_f32_e32 v123, v123, v73
	v_add_f32_e32 v122, v122, v123
	v_add_f32_e32 v167, v167, v122
	v_add_f32_e32 v122, v74, v75
	v_add_f32_e32 v123, v76, v77
	v_add_f32_e32 v122, v122, v78
	v_add_f32_e32 v123, v123, v79
	v_add_f32_e32 v122, v122, v80
	v_add_f32_e32 v123, v123, v81
	v_add_f32_e32 v122, v122, v123
	v_add_f32_e32 v167, v167, v122
